# wave_sum butterflies: in-row steps (xor 1,2,4,8) via v_add_f32_dpp instead of ds_bpermute round trips (34 chains, bit-identical); on top of v9
# speedup vs baseline: 1.0050x; 1.0007x over previous
; __device__ __forceinline__ unsigned pk2(float lo, float hi) { return f2bf(lo) | (f2bf(hi) << 16); }
; template <int PH>
; __device__ __forceinline__ void run_phase(const Args& args, LAS unsigned char* lds) {
;     ...
;             for (int row = gw; row < rend; row += NGW) {
;                 const int nrow = row + NGW;
;                 if (nrow < rend) { const float* xn = nrow < ML ? srcL + (size_t)nrow * D : srcC + (size_t)(nrow - ML) * D;
; #pragma unroll
;                     for (int j = 0; j < 8; ++j) nv[j] = ((const f32x4*)xn)[lane + 64 * j]; }
;                 const float* mr = modL + (row < ML ? (row >> 11) : 8) * MODW;
;                 float ss = 0.f;
; #pragma unroll
;                 for (int j = 0; j < 8; ++j) ss += (v[j].x * v[j].x + v[j].y * v[j].y) + (v[j].z * v[j].z + v[j].w * v[j].w);
;                 const float rs = 1.0f / sqrtf(wave_sum(ss) * (1.0f / D) + NEPS);
;                 u32x2* op = (u32x2*)(Hb + (size_t)row * D);
; #pragma unroll
;                 for (int j = 0; j < 8; ++j) { const int c4 = lane + 64 * j; const f32x4 gg = ((const f32x4*)g)[c4], sh = ((const f32x4*)mr)[c4], sc = ((const f32x4*)(mr + D))[c4];
;                     u32x2 w; w.x = pk2(v[j].x * rs * gg.x * (1.f + sc.x) + sh.x, v[j].y * rs * gg.y * (1.f + sc.y) + sh.y);
;                     w.y = pk2(v[j].z * rs * gg.z * (1.f + sc.z) + sh.z, v[j].w * rs * gg.w * (1.f + sc.w) + sh.w); op[c4] = w; }
.LBB0_151:
	s_waitcnt vmcnt(7)
	v_mov_b32_e32 v98, v61
	s_waitcnt vmcnt(6)
	v_mov_b32_e32 v99, v57
	v_mov_b32_e32 v96, v60
	v_mov_b32_e32 v97, v56
	v_pk_mul_f32 v[98:99], v[98:99], v[98:99]
	v_mov_b32_e32 v100, v63
	v_mov_b32_e32 v101, v59
	v_pk_fma_f32 v[96:97], v[96:97], v[96:97], v[98:99]
	v_mov_b32_e32 v98, v62
	v_mov_b32_e32 v99, v58
	v_pk_mul_f32 v[100:101], v[100:101], v[100:101]
	s_waitcnt vmcnt(3)
	v_mul_f32_e32 v80, v44, v44
	v_pk_fma_f32 v[98:99], v[98:99], v[98:99], v[100:101]
	v_pk_mul_f32 v[100:101], v[52:53], v[52:53]
	v_pk_add_f32 v[96:97], v[96:97], v[98:99]
	v_pk_mul_f32 v[98:99], v[54:55], v[54:55]
	v_pk_add_f32 v[96:97], v[96:97], v[96:97] op_sel:[0,1] op_sel_hi:[1,0]
	v_pk_mov_b32 v[102:103], v[100:101], v[98:99] op_sel:[1,0]
	v_mov_b32_e32 v101, v99
	v_pk_add_f32 v[98:99], v[102:103], v[100:101]
	v_mul_f32_e32 v100, v45, v45
	v_pk_add_f32 v[98:99], v[98:99], v[98:99] op_sel:[0,1] op_sel_hi:[1,0]
	v_mov_b32_e32 v97, v80
	v_mov_b32_e32 v99, v100
	v_mul_f32_e32 v80, v49, v49
	v_mul_f32_e32 v101, v46, v46
	v_pk_add_f32 v[96:97], v[96:97], v[98:99]
	v_pk_fma_f32 v[98:99], v[48:49], v[48:49], v[80:81] op_sel_hi:[1,1,0]
	v_mul_f32_e32 v80, v51, v51
	v_mul_f32_e32 v102, v47, v47
	v_mov_b32_e32 v99, v101
	v_pk_fma_f32 v[100:101], v[50:51], v[50:51], v[80:81] op_sel_hi:[1,1,0]
	s_add_i32 s25, s0, s2
	v_mov_b32_e32 v101, v102
	v_pk_add_f32 v[98:99], v[98:99], v[100:101]
	s_waitcnt vmcnt(2)
	v_pk_mul_f32 v[100:101], v[40:41], v[40:41]
	v_pk_add_f32 v[96:97], v[96:97], v[98:99]
	v_pk_mul_f32 v[98:99], v[42:43], v[42:43]
	s_min_i32 s0, s0, 0x4000
	v_pk_mov_b32 v[102:103], v[100:101], v[98:99] op_sel:[1,0]
	v_mov_b32_e32 v101, v99
	v_pk_add_f32 v[98:99], v[102:103], v[100:101]
	s_lshr_b32 s0, s0, 11
	s_waitcnt vmcnt(0)
	v_mul_f32_e32 v80, v0, v0
	v_mul_f32_e32 v100, v1, v1
	v_pk_add_f32 v[96:97], v[96:97], v[96:97] op_sel:[0,1] op_sel_hi:[1,0]
	v_pk_add_f32 v[98:99], v[98:99], v[98:99] op_sel:[0,1] op_sel_hi:[1,0]
	s_mulk_i32 s0, 0x3000
	v_mov_b32_e32 v97, v80
	v_mov_b32_e32 v99, v100
	v_mul_f32_e32 v80, v5, v5
	s_ashr_i32 s1, s0, 31
	v_mul_f32_e32 v101, v2, v2
	v_pk_add_f32 v[96:97], v[96:97], v[98:99]
	v_pk_fma_f32 v[98:99], v[4:5], v[4:5], v[80:81] op_sel_hi:[1,1,0]
	v_mul_f32_e32 v80, v7, v7
	v_mul_f32_e32 v102, v3, v3
	v_mov_b32_e32 v99, v101
	v_pk_fma_f32 v[100:101], v[6:7], v[6:7], v[80:81] op_sel_hi:[1,1,0]
	s_lshl_b64 s[0:1], s[0:1], 2
	v_mov_b32_e32 v101, v102
	s_add_u32 s6, s23, s0
	v_pk_add_f32 v[98:99], v[98:99], v[100:101]
	s_addc_u32 s7, s24, s1
	v_pk_add_f32 v[96:97], v[96:97], v[98:99]
	s_add_u32 s8, s6, 0x2000
	v_add_f32_e32 v80, v96, v97
	global_load_dwordx4 v[96:99], v[68:69], off
	s_addc_u32 s9, s7, 0
	global_load_dwordx4 v[100:103], v95, s[8:9]
	global_load_dwordx4 v[104:107], v95, s[6:7]
	ds_bpermute_b32 v108, v67, v80
	s_add_u32 s10, s10, s2
	s_addc_u32 s11, s11, s3
	s_cmpk_gt_i32 s25, 0x47ff
	s_waitcnt lgkmcnt(0)
	v_add_f32_e32 v80, v80, v108
	s_nop 1
	v_add_f32_dpp v80, v80, v80 quad_perm:[2,3,0,1] row_mask:0xf bank_mask:0xf
	s_nop 1
	v_add_f32_dpp v80, v80, v80 row_half_mirror row_mask:0xf bank_mask:0xf
	s_nop 1
	v_add_f32_dpp v80, v80, v80 row_mirror row_mask:0xf bank_mask:0xf
	ds_bpermute_b32 v108, v84, v80
	s_waitcnt lgkmcnt(0)
	v_add_f32_e32 v80, v80, v108
	ds_bpermute_b32 v108, v85, v80
	s_waitcnt lgkmcnt(0)
	v_add_f32_e32 v80, v80, v108
	v_fmamk_f32 v80, v80, 0x3a000000, v65
	v_mul_f32_e32 v108, 0x4f800000, v80
	v_cmp_gt_f32_e32 vcc, s14, v80
	s_waitcnt vmcnt(0)
	v_mov_b32_e32 v113, v106
	v_cndmask_b32_e32 v80, v80, v108, vcc
	v_sqrt_f32_e32 v108, v80
	v_mov_b32_e32 v106, v105
	v_mov_b32_e32 v105, v58
	v_mov_b32_e32 v58, v57
	v_add_u32_e32 v109, -1, v108
	v_fma_f32 v110, -v109, v108, v80
	v_cmp_ge_f32_e64 s[0:1], 0, v110
	v_add_u32_e32 v110, 1, v108
	s_nop 0
	v_cndmask_b32_e64 v109, v108, v109, s[0:1]
	v_fma_f32 v108, -v110, v108, v80
	v_cmp_lt_f32_e64 s[0:1], 0, v108
	s_nop 1
	v_cndmask_b32_e64 v108, v109, v110, s[0:1]
	v_mul_f32_e32 v109, 0x37800000, v108
	v_cndmask_b32_e32 v108, v108, v109, vcc
	v_cmp_class_f32_e32 vcc, v80, v86
	s_nop 1
	v_cndmask_b32_e32 v80, v108, v80, vcc
	v_div_scale_f32 v108, s[0:1], v80, v80, 1.0
	v_rcp_f32_e32 v109, v108
	s_mov_b32 s0, s25
	v_fma_f32 v110, -v108, v109, 1.0
	v_fmac_f32_e32 v109, v110, v109
	v_div_scale_f32 v110, vcc, 1.0, v80, 1.0
	v_mul_f32_e32 v111, v110, v109
	v_fma_f32 v112, -v108, v111, v110
	v_fmac_f32_e32 v111, v112, v109
	v_fma_f32 v108, -v108, v111, v110
	v_div_fmas_f32 v108, v108, v109, v111
	v_div_fixup_f32 v80, v108, v80, 1.0
	v_mov_b32_e32 v108, v60
	v_mov_b32_e32 v109, v62
	v_pk_mul_f32 v[108:109], v[108:109], v[80:81] op_sel_hi:[1,0]
	v_mov_b32_e32 v110, v96
	v_mov_b32_e32 v111, v98
	v_mov_b32_e32 v62, v61
	v_pk_mul_f32 v[108:109], v[110:111], v[108:109]
	v_mov_b32_e32 v111, v102
	v_pk_mul_f32 v[60:61], v[62:63], v[80:81] op_sel_hi:[1,0]
	v_mov_b32_e32 v98, v97
	v_mov_b32_e32 v102, v101
	v_mov_b32_e32 v110, v100
	v_pk_mul_f32 v[60:61], v[98:99], v[60:61]
	v_pk_add_f32 v[62:63], v[102:103], 1.0 op_sel_hi:[1,0]
	v_pk_add_f32 v[110:111], v[110:111], 1.0 op_sel_hi:[1,0]
	v_mov_b32_e32 v112, v104
	v_pk_fma_f32 v[60:61], v[62:63], v[60:61], v[106:107]
	v_pk_fma_f32 v[108:109], v[110:111], v[108:109], v[112:113]
	v_and_b32_sdwa v96, v61, v94 dst_sel:DWORD dst_unused:UNUSED_PAD src0_sel:WORD_1 src1_sel:DWORD
	v_and_b32_sdwa v97, v60, v94 dst_sel:DWORD dst_unused:UNUSED_PAD src0_sel:WORD_1 src1_sel:DWORD
	v_and_b32_sdwa v62, v109, v94 dst_sel:DWORD dst_unused:UNUSED_PAD src0_sel:WORD_1 src1_sel:DWORD
	v_and_b32_sdwa v63, v108, v94 dst_sel:DWORD dst_unused:UNUSED_PAD src0_sel:WORD_1 src1_sel:DWORD
	v_add3_u32 v61, v61, v96, s15
	v_add3_u32 v60, v60, v97, s15
	v_add3_u32 v63, v108, v63, s15
	v_add3_u32 v62, v109, v62, s15
	v_and_b32_e32 v61, 0xffff0000, v61
	v_and_b32_e32 v60, 0xffff0000, v60
	v_or_b32_sdwa v61, v61, v62 dst_sel:DWORD dst_unused:UNUSED_PAD src0_sel:DWORD src1_sel:WORD_1
	v_or_b32_sdwa v60, v60, v63 dst_sel:DWORD dst_unused:UNUSED_PAD src0_sel:DWORD src1_sel:WORD_1
	global_store_dwordx2 v[78:79], v[60:61], off offset:-2048
	global_load_dwordx4 v[60:63], v[68:69], off offset:1024
	s_nop 0
	global_load_dwordx4 v[96:99], v87, s[8:9]
	global_load_dwordx4 v[100:103], v95, s[6:7] offset:1024
	v_mov_b32_e32 v104, v56
	v_pk_mul_f32 v[56:57], v[104:105], v[80:81] op_sel_hi:[1,0]
	v_pk_mul_f32 v[58:59], v[58:59], v[80:81] op_sel_hi:[1,0]
	s_waitcnt vmcnt(2)
; __device__ __forceinline__ unsigned pk2(float lo, float hi) { return f2bf(lo) | (f2bf(hi) << 16); }
; template <int PH>
; __device__ __forceinline__ void run_phase(const Args& args, LAS unsigned char* lds) {
;     ...
; #pragma unroll
;                 for (int j = 0; j < 8; ++j) { const int c4 = lane + 64 * j; const f32x4 gg = ((const f32x4*)g)[c4], sh = ((const f32x4*)mr)[c4], sc = ((const f32x4*)(mr + D))[c4];
;                     u32x2 w; w.x = pk2(v[j].x * rs * gg.x * (1.f + sc.x) + sh.x, v[j].y * rs * gg.y * (1.f + sc.y) + sh.y);
;                     w.y = pk2(v[j].z * rs * gg.z * (1.f + sc.z) + sh.z, v[j].w * rs * gg.w * (1.f + sc.w) + sh.w); op[c4] = w; }
	v_mov_b32_e32 v105, v62
	s_waitcnt vmcnt(1)
	v_mov_b32_e32 v107, v98
	v_mov_b32_e32 v62, v61
	v_mov_b32_e32 v98, v97
	v_mov_b32_e32 v104, v60
	v_mov_b32_e32 v106, v96
	s_waitcnt vmcnt(0)
	v_mov_b32_e32 v109, v102
	v_mov_b32_e32 v102, v101
	v_pk_mul_f32 v[58:59], v[62:63], v[58:59]
	v_pk_add_f32 v[62:63], v[98:99], 1.0 op_sel_hi:[1,0]
	v_mov_b32_e32 v108, v100
	v_pk_mul_f32 v[56:57], v[104:105], v[56:57]
	v_pk_add_f32 v[60:61], v[106:107], 1.0 op_sel_hi:[1,0]
	v_pk_fma_f32 v[58:59], v[58:59], v[62:63], v[102:103]
	v_pk_fma_f32 v[56:57], v[56:57], v[60:61], v[108:109]
	v_and_b32_sdwa v62, v59, v94 dst_sel:DWORD dst_unused:UNUSED_PAD src0_sel:WORD_1 src1_sel:DWORD
	v_and_b32_sdwa v63, v58, v94 dst_sel:DWORD dst_unused:UNUSED_PAD src0_sel:WORD_1 src1_sel:DWORD
	v_and_b32_sdwa v60, v57, v94 dst_sel:DWORD dst_unused:UNUSED_PAD src0_sel:WORD_1 src1_sel:DWORD
	v_and_b32_sdwa v61, v56, v94 dst_sel:DWORD dst_unused:UNUSED_PAD src0_sel:WORD_1 src1_sel:DWORD
	v_add3_u32 v59, v59, v62, s15
	v_add3_u32 v58, v58, v63, s15
	v_add3_u32 v56, v56, v61, s15
	v_add3_u32 v57, v57, v60, s15
	v_and_b32_e32 v59, 0xffff0000, v59
	v_and_b32_e32 v58, 0xffff0000, v58
	v_or_b32_sdwa v57, v59, v57 dst_sel:DWORD dst_unused:UNUSED_PAD src0_sel:DWORD src1_sel:WORD_1
	v_or_b32_sdwa v56, v58, v56 dst_sel:DWORD dst_unused:UNUSED_PAD src0_sel:DWORD src1_sel:WORD_1
	global_store_dwordx2 v[78:79], v[56:57], off offset:-1536
	global_load_dwordx4 v[56:59], v[68:69], off offset:2048
	s_nop 0
	global_load_dwordx4 v[60:63], v88, s[8:9]
	global_load_dwordx4 v[96:99], v95, s[6:7] offset:2048
	v_mov_b32_e32 v100, v52
	v_mov_b32_e32 v101, v54
	v_mov_b32_e32 v54, v53
	v_pk_mul_f32 v[52:53], v[100:101], v[80:81] op_sel_hi:[1,0]
	v_pk_mul_f32 v[54:55], v[54:55], v[80:81] op_sel_hi:[1,0]
	s_waitcnt vmcnt(2)
	v_mov_b32_e32 v101, v58
	s_waitcnt vmcnt(1)
	v_mov_b32_e32 v103, v62
	v_mov_b32_e32 v58, v57
	v_mov_b32_e32 v62, v61
	v_mov_b32_e32 v100, v56
	v_mov_b32_e32 v102, v60
	s_waitcnt vmcnt(0)
	v_mov_b32_e32 v105, v98
	v_mov_b32_e32 v98, v97
	v_pk_mul_f32 v[54:55], v[54:55], v[58:59]
	v_pk_add_f32 v[58:59], v[62:63], 1.0 op_sel_hi:[1,0]
	v_mov_b32_e32 v104, v96
	v_pk_mul_f32 v[52:53], v[52:53], v[100:101]
	v_pk_add_f32 v[56:57], v[102:103], 1.0 op_sel_hi:[1,0]
	v_pk_fma_f32 v[54:55], v[54:55], v[58:59], v[98:99]
	v_pk_fma_f32 v[52:53], v[52:53], v[56:57], v[104:105]
	v_and_b32_sdwa v58, v55, v94 dst_sel:DWORD dst_unused:UNUSED_PAD src0_sel:WORD_1 src1_sel:DWORD
	v_and_b32_sdwa v59, v54, v94 dst_sel:DWORD dst_unused:UNUSED_PAD src0_sel:WORD_1 src1_sel:DWORD
	v_and_b32_sdwa v56, v53, v94 dst_sel:DWORD dst_unused:UNUSED_PAD src0_sel:WORD_1 src1_sel:DWORD
	v_and_b32_sdwa v57, v52, v94 dst_sel:DWORD dst_unused:UNUSED_PAD src0_sel:WORD_1 src1_sel:DWORD
	v_add3_u32 v55, v55, v58, s15
	v_add3_u32 v54, v54, v59, s15
	v_add3_u32 v52, v52, v57, s15
	v_add3_u32 v53, v53, v56, s15
	v_and_b32_e32 v55, 0xffff0000, v55
	v_and_b32_e32 v54, 0xffff0000, v54
	v_or_b32_sdwa v53, v55, v53 dst_sel:DWORD dst_unused:UNUSED_PAD src0_sel:DWORD src1_sel:WORD_1
	v_or_b32_sdwa v52, v54, v52 dst_sel:DWORD dst_unused:UNUSED_PAD src0_sel:DWORD src1_sel:WORD_1
	global_store_dwordx2 v[78:79], v[52:53], off offset:-1024
	global_load_dwordx4 v[52:55], v[68:69], off offset:3072
	s_nop 0
	global_load_dwordx4 v[56:59], v89, s[8:9]
	global_load_dwordx4 v[60:63], v95, s[6:7] offset:3072
	v_mov_b32_e32 v96, v48
	v_mov_b32_e32 v97, v50
	v_mov_b32_e32 v50, v49
	v_pk_mul_f32 v[48:49], v[96:97], v[80:81] op_sel_hi:[1,0]
	v_pk_mul_f32 v[50:51], v[50:51], v[80:81] op_sel_hi:[1,0]
	s_waitcnt vmcnt(2)
	v_mov_b32_e32 v97, v54
	s_waitcnt vmcnt(1)
	v_mov_b32_e32 v99, v58
	v_mov_b32_e32 v54, v53
	v_mov_b32_e32 v58, v57
	v_mov_b32_e32 v96, v52
	v_mov_b32_e32 v98, v56
	s_waitcnt vmcnt(0)
	v_mov_b32_e32 v101, v62
	v_mov_b32_e32 v62, v61
	v_pk_mul_f32 v[50:51], v[50:51], v[54:55]
	v_pk_add_f32 v[54:55], v[58:59], 1.0 op_sel_hi:[1,0]
	v_mov_b32_e32 v100, v60
	v_pk_mul_f32 v[48:49], v[48:49], v[96:97]
	v_pk_add_f32 v[52:53], v[98:99], 1.0 op_sel_hi:[1,0]
	v_pk_fma_f32 v[50:51], v[50:51], v[54:55], v[62:63]
	v_pk_fma_f32 v[48:49], v[48:49], v[52:53], v[100:101]
	v_and_b32_sdwa v54, v51, v94 dst_sel:DWORD dst_unused:UNUSED_PAD src0_sel:WORD_1 src1_sel:DWORD
	v_and_b32_sdwa v55, v50, v94 dst_sel:DWORD dst_unused:UNUSED_PAD src0_sel:WORD_1 src1_sel:DWORD
	v_and_b32_sdwa v52, v49, v94 dst_sel:DWORD dst_unused:UNUSED_PAD src0_sel:WORD_1 src1_sel:DWORD
	v_and_b32_sdwa v53, v48, v94 dst_sel:DWORD dst_unused:UNUSED_PAD src0_sel:WORD_1 src1_sel:DWORD
	v_add3_u32 v51, v51, v54, s15
	v_add3_u32 v50, v50, v55, s15
	v_add3_u32 v48, v48, v53, s15
	v_add3_u32 v49, v49, v52, s15
	v_and_b32_e32 v51, 0xffff0000, v51
	v_and_b32_e32 v50, 0xffff0000, v50
	v_or_b32_sdwa v49, v51, v49 dst_sel:DWORD dst_unused:UNUSED_PAD src0_sel:DWORD src1_sel:WORD_1
	v_or_b32_sdwa v48, v50, v48 dst_sel:DWORD dst_unused:UNUSED_PAD src0_sel:DWORD src1_sel:WORD_1
	global_store_dwordx2 v[78:79], v[48:49], off offset:-512
	global_load_dwordx4 v[48:51], v[70:71], off
	s_nop 0
	global_load_dwordx4 v[52:55], v90, s[8:9]
	global_load_dwordx4 v[56:59], v90, s[6:7]
	v_mov_b32_e32 v60, v44
	v_mov_b32_e32 v61, v46
	v_mov_b32_e32 v46, v45
	v_pk_mul_f32 v[44:45], v[60:61], v[80:81] op_sel_hi:[1,0]
	v_pk_mul_f32 v[46:47], v[46:47], v[80:81] op_sel_hi:[1,0]
	s_waitcnt vmcnt(2)
	v_mov_b32_e32 v61, v50
	s_waitcnt vmcnt(1)
	v_mov_b32_e32 v63, v54
	v_mov_b32_e32 v50, v49
	v_mov_b32_e32 v54, v53
	v_mov_b32_e32 v60, v48
	v_mov_b32_e32 v62, v52
	s_waitcnt vmcnt(0)
; __device__ __forceinline__ unsigned pk2(float lo, float hi) { return f2bf(lo) | (f2bf(hi) << 16); }
; template <int PH>
; __device__ __forceinline__ void run_phase(const Args& args, LAS unsigned char* lds) {
;     ...
; #pragma unroll
;                 for (int j = 0; j < 8; ++j) { const int c4 = lane + 64 * j; const f32x4 gg = ((const f32x4*)g)[c4], sh = ((const f32x4*)mr)[c4], sc = ((const f32x4*)(mr + D))[c4];
;                     u32x2 w; w.x = pk2(v[j].x * rs * gg.x * (1.f + sc.x) + sh.x, v[j].y * rs * gg.y * (1.f + sc.y) + sh.y);
;                     w.y = pk2(v[j].z * rs * gg.z * (1.f + sc.z) + sh.z, v[j].w * rs * gg.w * (1.f + sc.w) + sh.w); op[c4] = w; }
; #pragma unroll
;                 for (int j = 0; j < 8; ++j) v[j] = nv[j];
;             }
	v_mov_b32_e32 v97, v58
	v_mov_b32_e32 v58, v57
	v_pk_mul_f32 v[46:47], v[46:47], v[50:51]
	v_pk_add_f32 v[50:51], v[54:55], 1.0 op_sel_hi:[1,0]
	v_mov_b32_e32 v96, v56
	v_pk_mul_f32 v[44:45], v[44:45], v[60:61]
	v_pk_add_f32 v[48:49], v[62:63], 1.0 op_sel_hi:[1,0]
	v_pk_fma_f32 v[46:47], v[46:47], v[50:51], v[58:59]
	v_pk_fma_f32 v[44:45], v[44:45], v[48:49], v[96:97]
	v_and_b32_sdwa v50, v47, v94 dst_sel:DWORD dst_unused:UNUSED_PAD src0_sel:WORD_1 src1_sel:DWORD
	v_and_b32_sdwa v51, v46, v94 dst_sel:DWORD dst_unused:UNUSED_PAD src0_sel:WORD_1 src1_sel:DWORD
	v_and_b32_sdwa v48, v45, v94 dst_sel:DWORD dst_unused:UNUSED_PAD src0_sel:WORD_1 src1_sel:DWORD
	v_and_b32_sdwa v49, v44, v94 dst_sel:DWORD dst_unused:UNUSED_PAD src0_sel:WORD_1 src1_sel:DWORD
	v_add3_u32 v47, v47, v50, s15
	v_add3_u32 v46, v46, v51, s15
	v_add3_u32 v44, v44, v49, s15
	v_add3_u32 v45, v45, v48, s15
	v_and_b32_e32 v47, 0xffff0000, v47
	v_and_b32_e32 v46, 0xffff0000, v46
	v_or_b32_sdwa v45, v47, v45 dst_sel:DWORD dst_unused:UNUSED_PAD src0_sel:DWORD src1_sel:WORD_1
	v_or_b32_sdwa v44, v46, v44 dst_sel:DWORD dst_unused:UNUSED_PAD src0_sel:DWORD src1_sel:WORD_1
	global_store_dwordx2 v[78:79], v[44:45], off
	global_load_dwordx4 v[44:47], v[72:73], off
	s_nop 0
	global_load_dwordx4 v[48:51], v91, s[8:9]
	global_load_dwordx4 v[52:55], v91, s[6:7]
	v_mov_b32_e32 v56, v40
	v_mov_b32_e32 v57, v42
	v_mov_b32_e32 v42, v41
	v_pk_mul_f32 v[40:41], v[56:57], v[80:81] op_sel_hi:[1,0]
	v_pk_mul_f32 v[42:43], v[42:43], v[80:81] op_sel_hi:[1,0]
	s_waitcnt vmcnt(2)
	v_mov_b32_e32 v57, v46
	s_waitcnt vmcnt(1)
	v_mov_b32_e32 v59, v50
	v_mov_b32_e32 v46, v45
	v_mov_b32_e32 v50, v49
	v_mov_b32_e32 v56, v44
	v_mov_b32_e32 v58, v48
	s_waitcnt vmcnt(0)
	v_mov_b32_e32 v61, v54
	v_mov_b32_e32 v54, v53
	v_pk_mul_f32 v[42:43], v[42:43], v[46:47]
	v_pk_add_f32 v[46:47], v[50:51], 1.0 op_sel_hi:[1,0]
	v_mov_b32_e32 v60, v52
	v_pk_mul_f32 v[40:41], v[40:41], v[56:57]
	v_pk_add_f32 v[44:45], v[58:59], 1.0 op_sel_hi:[1,0]
	v_pk_fma_f32 v[42:43], v[42:43], v[46:47], v[54:55]
	v_pk_fma_f32 v[40:41], v[40:41], v[44:45], v[60:61]
	v_and_b32_sdwa v46, v43, v94 dst_sel:DWORD dst_unused:UNUSED_PAD src0_sel:WORD_1 src1_sel:DWORD
	v_and_b32_sdwa v47, v42, v94 dst_sel:DWORD dst_unused:UNUSED_PAD src0_sel:WORD_1 src1_sel:DWORD
	v_and_b32_sdwa v44, v41, v94 dst_sel:DWORD dst_unused:UNUSED_PAD src0_sel:WORD_1 src1_sel:DWORD
	v_and_b32_sdwa v45, v40, v94 dst_sel:DWORD dst_unused:UNUSED_PAD src0_sel:WORD_1 src1_sel:DWORD
	v_add3_u32 v43, v43, v46, s15
	v_add3_u32 v42, v42, v47, s15
	v_add3_u32 v40, v40, v45, s15
	v_add3_u32 v41, v41, v44, s15
	v_and_b32_e32 v43, 0xffff0000, v43
	v_and_b32_e32 v42, 0xffff0000, v42
	v_or_b32_sdwa v41, v43, v41 dst_sel:DWORD dst_unused:UNUSED_PAD src0_sel:DWORD src1_sel:WORD_1
	v_or_b32_sdwa v40, v42, v40 dst_sel:DWORD dst_unused:UNUSED_PAD src0_sel:DWORD src1_sel:WORD_1
	global_store_dwordx2 v[78:79], v[40:41], off offset:512
	global_load_dwordx4 v[40:43], v[74:75], off
	s_nop 0
	global_load_dwordx4 v[44:47], v92, s[8:9]
	global_load_dwordx4 v[48:51], v92, s[6:7]
	v_mov_b32_e32 v52, v4
	v_mov_b32_e32 v53, v6
	v_mov_b32_e32 v6, v5
	v_pk_mul_f32 v[4:5], v[52:53], v[80:81] op_sel_hi:[1,0]
	v_pk_mul_f32 v[6:7], v[6:7], v[80:81] op_sel_hi:[1,0]
	v_mov_b64_e32 v[62:63], v[38:39]
	v_mov_b64_e32 v[60:61], v[36:37]
	s_waitcnt vmcnt(2)
	v_mov_b32_e32 v53, v42
	s_waitcnt vmcnt(1)
	v_mov_b32_e32 v55, v46
	v_mov_b32_e32 v42, v41
	v_mov_b32_e32 v46, v45
	v_mov_b32_e32 v52, v40
	v_mov_b32_e32 v54, v44
	s_waitcnt vmcnt(0)
	v_mov_b32_e32 v57, v50
	v_mov_b32_e32 v50, v49
	v_pk_mul_f32 v[6:7], v[6:7], v[42:43]
	v_pk_add_f32 v[42:43], v[46:47], 1.0 op_sel_hi:[1,0]
	v_mov_b32_e32 v56, v48
	v_pk_mul_f32 v[4:5], v[4:5], v[52:53]
	v_pk_add_f32 v[40:41], v[54:55], 1.0 op_sel_hi:[1,0]
	v_pk_fma_f32 v[6:7], v[6:7], v[42:43], v[50:51]
	v_pk_fma_f32 v[4:5], v[4:5], v[40:41], v[56:57]
	v_and_b32_sdwa v42, v7, v94 dst_sel:DWORD dst_unused:UNUSED_PAD src0_sel:WORD_1 src1_sel:DWORD
	v_and_b32_sdwa v43, v6, v94 dst_sel:DWORD dst_unused:UNUSED_PAD src0_sel:WORD_1 src1_sel:DWORD
	v_and_b32_sdwa v40, v5, v94 dst_sel:DWORD dst_unused:UNUSED_PAD src0_sel:WORD_1 src1_sel:DWORD
	v_and_b32_sdwa v41, v4, v94 dst_sel:DWORD dst_unused:UNUSED_PAD src0_sel:WORD_1 src1_sel:DWORD
	v_add3_u32 v7, v7, v42, s15
	v_add3_u32 v6, v6, v43, s15
	v_add3_u32 v4, v4, v41, s15
	v_add3_u32 v5, v5, v40, s15
	v_and_b32_e32 v7, 0xffff0000, v7
	v_and_b32_e32 v6, 0xffff0000, v6
	v_or_b32_sdwa v5, v7, v5 dst_sel:DWORD dst_unused:UNUSED_PAD src0_sel:DWORD src1_sel:WORD_1
	v_or_b32_sdwa v4, v6, v4 dst_sel:DWORD dst_unused:UNUSED_PAD src0_sel:DWORD src1_sel:WORD_1
	global_store_dwordx2 v[78:79], v[4:5], off offset:1024
	global_load_dwordx4 v[96:99], v[76:77], off
	global_load_dwordx4 v[100:103], v93, s[8:9]
	global_load_dwordx4 v[104:107], v93, s[6:7]
	v_mov_b32_e32 v4, v0
	v_mov_b32_e32 v5, v2
	v_mov_b32_e32 v2, v1
	v_pk_mul_f32 v[108:109], v[4:5], v[80:81] op_sel_hi:[1,0]
	v_pk_mul_f32 v[110:111], v[2:3], v[80:81] op_sel_hi:[1,0]
	v_mov_b64_e32 v[58:59], v[34:35]
	v_mov_b64_e32 v[54:55], v[30:31]
	v_mov_b64_e32 v[50:51], v[26:27]
	v_mov_b64_e32 v[46:47], v[22:23]
	v_mov_b64_e32 v[42:43], v[18:19]
	v_mov_b64_e32 v[4:5], v[12:13]
	v_mov_b64_e32 v[0:1], v[8:9]
	v_mov_b64_e32 v[56:57], v[32:33]
	v_mov_b64_e32 v[52:53], v[28:29]
	v_mov_b64_e32 v[48:49], v[24:25]
	v_mov_b64_e32 v[44:45], v[20:21]
	v_mov_b64_e32 v[40:41], v[16:17]
	v_mov_b64_e32 v[6:7], v[14:15]
	v_mov_b64_e32 v[2:3], v[10:11]
	s_waitcnt vmcnt(2)
	v_mov_b32_e32 v112, v96
	v_mov_b32_e32 v113, v98
	s_waitcnt vmcnt(1)
	v_mov_b32_e32 v114, v100
	v_mov_b32_e32 v115, v102
	v_mov_b32_e32 v98, v97
	v_mov_b32_e32 v102, v101
	s_waitcnt vmcnt(0)
	v_mov_b32_e32 v116, v104
	v_mov_b32_e32 v117, v106
	v_mov_b32_e32 v106, v105
	v_pk_mul_f32 v[96:97], v[108:109], v[112:113]
	v_pk_add_f32 v[100:101], v[114:115], 1.0 op_sel_hi:[1,0]
	v_pk_mul_f32 v[98:99], v[110:111], v[98:99]
	v_pk_add_f32 v[102:103], v[102:103], 1.0 op_sel_hi:[1,0]
	v_pk_fma_f32 v[96:97], v[96:97], v[100:101], v[116:117]
	v_pk_fma_f32 v[98:99], v[98:99], v[102:103], v[106:107]
	v_and_b32_sdwa v80, v97, v94 dst_sel:DWORD dst_unused:UNUSED_PAD src0_sel:WORD_1 src1_sel:DWORD
	v_and_b32_sdwa v95, v96, v94 dst_sel:DWORD dst_unused:UNUSED_PAD src0_sel:WORD_1 src1_sel:DWORD
	v_and_b32_sdwa v100, v99, v94 dst_sel:DWORD dst_unused:UNUSED_PAD src0_sel:WORD_1 src1_sel:DWORD
	v_and_b32_sdwa v101, v98, v94 dst_sel:DWORD dst_unused:UNUSED_PAD src0_sel:WORD_1 src1_sel:DWORD
	v_add3_u32 v95, v96, v95, s15
	v_add3_u32 v80, v97, v80, s15
	v_add3_u32 v96, v99, v100, s15
	v_add3_u32 v97, v98, v101, s15
	v_and_b32_e32 v96, 0xffff0000, v96
	v_and_b32_e32 v98, 0xffff0000, v97
	v_or_b32_sdwa v97, v96, v80 dst_sel:DWORD dst_unused:UNUSED_PAD src0_sel:DWORD src1_sel:WORD_1
	v_or_b32_sdwa v96, v98, v95 dst_sel:DWORD dst_unused:UNUSED_PAD src0_sel:DWORD src1_sel:WORD_1
	global_store_dwordx2 v[78:79], v[96:97], off offset:1536
	v_lshl_add_u64 v[78:79], v[78:79], 0, s[4:5]
	s_cbranch_scc1 .LBB0_154

; #define LAS __attribute__((address_space(3)))
; template <int PH>
; __device__ __forceinline__ void run_phase(const Args& args, LAS unsigned char* lds) {
;     ...
;                     for (int r = 0; r < 9; ++r) { float a = 0.f;
; #pragma unroll
;                         for (int i = 0; i < 8; ++i) { const f32x4 sv = *(const LAS f32x4*)(shl + r * 2048 + 4 * (lane + 64 * i)); a += (wf[4 * i] * sv.x + wf[4 * i + 1] * sv.y) + (wf[4 * i + 2] * sv.z + wf[4 * i + 3] * sv.w); }
;                         const float t = wave_sum(a); if (lane == 0) dst[r * N + n] = t; }
.LBB0_163:
	v_add_u32_e32 v55, s1, v4
	s_waitcnt lgkmcnt(0)
	ds_read_b128 v[56:59], v55
	ds_read_b128 v[60:63], v55 offset:1024
	s_waitcnt lgkmcnt(1)
	v_mul_f32_e32 v57, v57, v24
	v_mul_f32_e32 v59, v59, v26
	v_fmac_f32_e32 v57, v56, v23
	v_fmac_f32_e32 v59, v58, v25
	s_waitcnt lgkmcnt(0)
	v_mul_f32_e32 v61, v61, v28
	v_add_f32_e32 v56, v57, v59
	v_add_f32_e32 v64, 0, v56
	v_fmac_f32_e32 v61, v60, v27
	v_mul_f32_e32 v60, v63, v30
	ds_read_b128 v[56:59], v55 offset:2048
	v_fmac_f32_e32 v60, v62, v29
	v_add_f32_e32 v60, v61, v60
	v_add_f32_e32 v64, v64, v60
	ds_read_b128 v[60:63], v55 offset:3072
	s_waitcnt lgkmcnt(1)
	v_mul_f32_e32 v57, v57, v32
	v_fmac_f32_e32 v57, v56, v31
	v_mul_f32_e32 v56, v59, v34
	v_fmac_f32_e32 v56, v58, v33
	v_add_f32_e32 v56, v57, v56
	s_waitcnt lgkmcnt(0)
	v_mul_f32_e32 v61, v61, v36
	v_add_f32_e32 v64, v64, v56
	v_fmac_f32_e32 v61, v60, v35
	v_mul_f32_e32 v60, v63, v38
	ds_read_b128 v[56:59], v55 offset:4096
	v_fmac_f32_e32 v60, v62, v37
	v_add_f32_e32 v60, v61, v60
	v_add_f32_e32 v64, v64, v60
	ds_read_b128 v[60:63], v55 offset:5120
	s_waitcnt lgkmcnt(1)
	v_mul_f32_e32 v57, v57, v40
	v_fmac_f32_e32 v57, v56, v39
	v_mul_f32_e32 v56, v59, v42
	v_fmac_f32_e32 v56, v58, v41
	v_add_f32_e32 v56, v57, v56
	s_waitcnt lgkmcnt(0)
	v_mul_f32_e32 v61, v61, v44
	v_add_f32_e32 v64, v64, v56
	v_fmac_f32_e32 v61, v60, v43
	v_mul_f32_e32 v60, v63, v46
	ds_read_b128 v[56:59], v55 offset:6144
	v_fmac_f32_e32 v60, v62, v45
	v_add_f32_e32 v60, v61, v60
	v_add_f32_e32 v64, v64, v60
	ds_read_b128 v[60:63], v55 offset:7168
	s_waitcnt lgkmcnt(1)
	v_mul_f32_e32 v55, v57, v48
	v_fmac_f32_e32 v55, v56, v47
	v_mul_f32_e32 v56, v59, v50
	v_fmac_f32_e32 v56, v58, v49
	v_add_f32_e32 v55, v55, v56
	s_waitcnt lgkmcnt(0)
	v_mul_f32_e32 v56, v61, v52
	v_mul_f32_e32 v57, v63, v54
	v_fmac_f32_e32 v56, v60, v51
	v_fmac_f32_e32 v57, v62, v53
	v_add_f32_e32 v55, v64, v55
	v_add_f32_e32 v56, v56, v57
	v_add_f32_e32 v55, v55, v56
	s_nop 1
	v_add_f32_dpp v55, v55, v55 quad_perm:[1,0,3,2] row_mask:0xf bank_mask:0xf
	s_nop 1
	v_add_f32_dpp v55, v55, v55 quad_perm:[2,3,0,1] row_mask:0xf bank_mask:0xf
	s_nop 1
	v_add_f32_dpp v55, v55, v55 row_half_mirror row_mask:0xf bank_mask:0xf
	s_nop 1
	v_add_f32_dpp v55, v55, v55 row_mirror row_mask:0xf bank_mask:0xf
	ds_bpermute_b32 v56, v21, v55
	s_waitcnt lgkmcnt(0)
	v_add_f32_e32 v55, v55, v56
	ds_bpermute_b32 v56, v22, v55
	s_and_saveexec_b64 s[8:9], vcc
	s_cbranch_execz .LBB0_162
	s_ashr_i32 s7, s6, 31
	s_lshl_b64 s[34:35], s[6:7], 2
	s_add_u32 s34, s11, s34
	s_addc_u32 s35, s14, s35
	s_waitcnt lgkmcnt(0)
	v_add_f32_e32 v55, v55, v56
	global_store_dword v65, v55, s[34:35]
	s_branch .LBB0_162

; template <int PH>
; __device__ __forceinline__ void run_phase(const Args& args, LAS unsigned char* lds) {
;     ...
;                         for (int k = 0; k < 8; ++k) { const int i = 8 * ch + k; if (i < 46) { const int q = p0 - 15 + i; float u0 = 0.f, u1 = 0.f;
;                             if (q >= 0 && q < L) { u0 = bflo(ca[k]) * __builtin_amdgcn_rcpf(1.0f + __expf(-bflo(cgt[k]))); u1 = bfhi(ca[k]) * __builtin_amdgcn_rcpf(1.0f + __expf(-bfhi(cgt[k]))); }
; #pragma unroll
;                             for (int o = 0; o < 16; ++o) { const int kk = i - o; if (kk >= 0 && kk <= 30) { a0[o] += w0[kk] * u0; a1[o] += w1[kk] * u1; } } } }
; #pragma unroll
;                         for (int k = 0; k < 8; ++k) { ca[k] = na[k]; cgt[k] = ng[k]; }
;                     }
;     ...
;                     float mean[16], rstd[16];
; #pragma unroll
;                     for (int o = 0; o < 16; ++o) { const float s = wave_sum(a0[o] + a1[o]); if (lane == 0) red[wave * 16 + o] = s; }
.LBB0_391:
	s_or_b64 exec, exec, s[0:1]
	v_fma_f32 v38, v188, v38, v198
	v_fma_f32 v39, v189, v39, v199
	v_fma_f32 v38, v130, v30, v38
	v_fma_f32 v39, v131, v31, v39
	v_fma_f32 v38, v132, v32, v38
	v_fma_f32 v39, v133, v33, v39
	v_fma_f32 v38, v134, v20, v38
	v_fma_f32 v39, v135, v21, v39
	v_fma_f32 v38, v136, v28, v38
	v_fma_f32 v39, v137, v29, v39
	v_fma_f32 v38, v138, v14, v38
	v_fma_f32 v39, v139, v15, v39
	v_fma_f32 v38, v140, v18, v38
	v_fma_f32 v39, v141, v19, v39
	v_fma_f32 v38, v142, v8, v38
	v_fma_f32 v39, v143, v9, v39
	v_fma_f32 v38, v144, v22, v38
	v_fma_f32 v39, v145, v23, v39
	v_fma_f32 v38, v146, v12, v38
	v_fma_f32 v39, v147, v13, v39
	v_fma_f32 v38, v148, v16, v38
	v_fma_f32 v39, v149, v17, v39
	v_fma_f32 v38, v150, v6, v38
	v_fma_f32 v39, v151, v7, v39
	v_fma_f32 v38, v152, v10, v38
	v_fma_f32 v39, v153, v11, v39
	v_fma_f32 v38, v154, v0, v38
	v_fma_f32 v39, v155, v1, v39
	v_fma_f32 v38, v156, v4, v38
	v_fma_f32 v39, v157, v5, v39
	v_fma_f32 v38, v158, v2, v38
	v_fma_f32 v39, v159, v3, v39
	v_fma_f32 v38, v160, v26, v38
	v_fma_f32 v39, v161, v27, v39
	v_fma_f32 v38, v162, v24, v38
	v_fma_f32 v39, v163, v25, v39
	v_fma_f32 v38, v164, v36, v38
	v_fma_f32 v39, v165, v37, v39
	v_fma_f32 v38, v166, v34, v38
	v_fma_f32 v39, v167, v35, v39
	v_fma_f32 v38, v168, v42, v38
	v_fma_f32 v39, v169, v43, v39
	v_fma_f32 v38, v170, v40, v38
	v_fma_f32 v39, v171, v41, v39
	v_fma_f32 v38, v172, v48, v38
	v_fma_f32 v39, v173, v49, v39
	v_fma_f32 v38, v174, v46, v38
	v_fma_f32 v39, v175, v47, v39
	v_fma_f32 v38, v176, v52, v38
	v_fma_f32 v39, v177, v53, v39
	v_fma_f32 v38, v178, v50, v38
	v_fma_f32 v39, v179, v51, v39
	v_fma_f32 v38, v180, v56, v38
	v_fma_f32 v39, v181, v57, v39
	v_fma_f32 v38, v182, v54, v38
	v_fma_f32 v39, v183, v55, v39
	v_fma_f32 v38, v186, v60, v38
	v_fma_f32 v39, v187, v61, v39
	v_fma_f32 v38, v190, v58, v38
	v_fma_f32 v39, v191, v59, v39
	v_fma_f32 v206, v194, v64, v38
	v_fma_f32 v207, v195, v65, v39
	v_add_f32_e32 v38, v206, v207
	s_nop 1
	v_add_f32_dpp v38, v38, v38 quad_perm:[1,0,3,2] row_mask:0xf bank_mask:0xf
	s_nop 1
	v_add_f32_dpp v38, v38, v38 quad_perm:[2,3,0,1] row_mask:0xf bank_mask:0xf
	s_nop 1
	v_add_f32_dpp v38, v38, v38 row_half_mirror row_mask:0xf bank_mask:0xf
	s_nop 1
	v_add_f32_dpp v38, v38, v38 row_mirror row_mask:0xf bank_mask:0xf
	ds_bpermute_b32 v39, v242, v38
	s_waitcnt lgkmcnt(0)
	v_add_f32_e32 v38, v38, v39
	ds_bpermute_b32 v39, v243, v38
	s_and_saveexec_b64 s[0:1], s[2:3]
	s_cbranch_execz .LBB0_393
	s_add_i32 s4, s10, 0
	s_waitcnt lgkmcnt(0)
	v_add_f32_e32 v38, v38, v39
	v_mov_b32_e32 v39, s4
	ds_write_b32 v39, v38 offset:4
.LBB0_393:
	s_or_b64 exec, exec, s[0:1]
	v_fma_f32 v30, v188, v30, v198
	v_fma_f32 v31, v189, v31, v199
	v_fma_f32 v30, v130, v32, v30
	v_fma_f32 v31, v131, v33, v31
	v_fma_f32 v30, v132, v20, v30
	v_fma_f32 v31, v133, v21, v31
	v_fma_f32 v30, v134, v28, v30
	v_fma_f32 v31, v135, v29, v31
	v_fma_f32 v30, v136, v14, v30
	v_fma_f32 v31, v137, v15, v31
	v_fma_f32 v30, v138, v18, v30
	v_fma_f32 v31, v139, v19, v31
	v_fma_f32 v30, v140, v8, v30
	v_fma_f32 v31, v141, v9, v31
	v_fma_f32 v30, v142, v22, v30
	v_fma_f32 v31, v143, v23, v31
	v_fma_f32 v30, v144, v12, v30
	v_fma_f32 v31, v145, v13, v31
	v_fma_f32 v30, v146, v16, v30
	v_fma_f32 v31, v147, v17, v31
	v_fma_f32 v30, v148, v6, v30
	v_fma_f32 v31, v149, v7, v31
	v_fma_f32 v30, v150, v10, v30
	v_fma_f32 v31, v151, v11, v31
	v_fma_f32 v30, v152, v0, v30
	v_fma_f32 v31, v153, v1, v31
	v_fma_f32 v30, v154, v4, v30
	v_fma_f32 v31, v155, v5, v31
	v_fma_f32 v30, v156, v2, v30
	v_fma_f32 v31, v157, v3, v31
	v_fma_f32 v30, v158, v26, v30
	v_fma_f32 v31, v159, v27, v31
	v_fma_f32 v30, v160, v24, v30
	v_fma_f32 v31, v161, v25, v31
	v_fma_f32 v30, v162, v36, v30
	v_fma_f32 v31, v163, v37, v31
	v_fma_f32 v30, v164, v34, v30
	v_fma_f32 v31, v165, v35, v31
	v_fma_f32 v30, v166, v42, v30
	v_fma_f32 v31, v167, v43, v31
	v_fma_f32 v30, v168, v40, v30
	v_fma_f32 v31, v169, v41, v31
	v_fma_f32 v30, v170, v48, v30
	v_fma_f32 v31, v171, v49, v31
	v_fma_f32 v30, v172, v46, v30
	v_fma_f32 v31, v173, v47, v31
	v_fma_f32 v30, v174, v52, v30
	v_fma_f32 v31, v175, v53, v31
	v_fma_f32 v30, v176, v50, v30
	v_fma_f32 v31, v177, v51, v31
	v_fma_f32 v30, v178, v56, v30
	v_fma_f32 v31, v179, v57, v31
	v_fma_f32 v30, v180, v54, v30
	v_fma_f32 v31, v181, v55, v31
	v_fma_f32 v30, v182, v60, v30
	v_fma_f32 v31, v183, v61, v31
	v_fma_f32 v30, v186, v58, v30
	v_fma_f32 v31, v187, v59, v31
	v_fma_f32 v30, v190, v64, v30
	v_fma_f32 v31, v191, v65, v31
	v_fma_f32 v208, v194, v62, v30
	v_fma_f32 v209, v195, v63, v31
	v_add_f32_e32 v30, v208, v209
	s_nop 1
	v_add_f32_dpp v30, v30, v30 quad_perm:[1,0,3,2] row_mask:0xf bank_mask:0xf
	s_nop 1
	v_add_f32_dpp v30, v30, v30 quad_perm:[2,3,0,1] row_mask:0xf bank_mask:0xf
	s_nop 1
	v_add_f32_dpp v30, v30, v30 row_half_mirror row_mask:0xf bank_mask:0xf
	s_nop 1
	v_add_f32_dpp v30, v30, v30 row_mirror row_mask:0xf bank_mask:0xf
	ds_bpermute_b32 v31, v242, v30
	s_waitcnt lgkmcnt(0)
	v_add_f32_e32 v30, v30, v31
	ds_bpermute_b32 v31, v243, v30
	s_and_saveexec_b64 s[0:1], s[2:3]
	s_cbranch_execz .LBB0_395
	s_add_i32 s4, s10, 0
	s_waitcnt lgkmcnt(0)
	v_add_f32_e32 v30, v30, v31
	v_mov_b32_e32 v31, s4
	ds_write_b32 v31, v30 offset:8
; template <int PH>
; __device__ __forceinline__ void run_phase(const Args& args, LAS unsigned char* lds) {
;     ...
;                         for (int k = 0; k < 8; ++k) { const int i = 8 * ch + k; if (i < 46) { const int q = p0 - 15 + i; float u0 = 0.f, u1 = 0.f;
;                             if (q >= 0 && q < L) { u0 = bflo(ca[k]) * __builtin_amdgcn_rcpf(1.0f + __expf(-bflo(cgt[k]))); u1 = bfhi(ca[k]) * __builtin_amdgcn_rcpf(1.0f + __expf(-bfhi(cgt[k]))); }
; #pragma unroll
;                             for (int o = 0; o < 16; ++o) { const int kk = i - o; if (kk >= 0 && kk <= 30) { a0[o] += w0[kk] * u0; a1[o] += w1[kk] * u1; } } } }
; #pragma unroll
;                         for (int k = 0; k < 8; ++k) { ca[k] = na[k]; cgt[k] = ng[k]; }
;                     }
;     ...
;                     float mean[16], rstd[16];
; #pragma unroll
;                     for (int o = 0; o < 16; ++o) { const float s = wave_sum(a0[o] + a1[o]); if (lane == 0) red[wave * 16 + o] = s; }
.LBB0_395:
	s_or_b64 exec, exec, s[0:1]
	s_waitcnt lgkmcnt(0)
	v_fma_f32 v30, v188, v32, v198
	v_fma_f32 v31, v189, v33, v199
	v_fma_f32 v30, v130, v20, v30
	v_fma_f32 v31, v131, v21, v31
	v_fma_f32 v30, v132, v28, v30
	v_fma_f32 v31, v133, v29, v31
	v_fma_f32 v30, v134, v14, v30
	v_fma_f32 v31, v135, v15, v31
	v_fma_f32 v30, v136, v18, v30
	v_fma_f32 v31, v137, v19, v31
	v_fma_f32 v30, v138, v8, v30
	v_fma_f32 v31, v139, v9, v31
	v_fma_f32 v30, v140, v22, v30
	v_fma_f32 v31, v141, v23, v31
	v_fma_f32 v30, v142, v12, v30
	v_fma_f32 v31, v143, v13, v31
	v_fma_f32 v30, v144, v16, v30
	v_fma_f32 v31, v145, v17, v31
	v_fma_f32 v30, v146, v6, v30
	v_fma_f32 v31, v147, v7, v31
	v_fma_f32 v30, v148, v10, v30
	v_fma_f32 v31, v149, v11, v31
	v_fma_f32 v30, v150, v0, v30
	v_fma_f32 v31, v151, v1, v31
	v_fma_f32 v30, v152, v4, v30
	v_fma_f32 v31, v153, v5, v31
	v_fma_f32 v30, v154, v2, v30
	v_fma_f32 v31, v155, v3, v31
	v_fma_f32 v30, v156, v26, v30
	v_fma_f32 v31, v157, v27, v31
	v_fma_f32 v30, v158, v24, v30
	v_fma_f32 v31, v159, v25, v31
	v_fma_f32 v30, v160, v36, v30
	v_fma_f32 v31, v161, v37, v31
	v_fma_f32 v30, v162, v34, v30
	v_fma_f32 v31, v163, v35, v31
	v_fma_f32 v30, v164, v42, v30
	v_fma_f32 v31, v165, v43, v31
	v_fma_f32 v30, v166, v40, v30
	v_fma_f32 v31, v167, v41, v31
	v_fma_f32 v30, v168, v48, v30
	v_fma_f32 v31, v169, v49, v31
	v_fma_f32 v30, v170, v46, v30
	v_fma_f32 v31, v171, v47, v31
	v_fma_f32 v30, v172, v52, v30
	v_fma_f32 v31, v173, v53, v31
	v_fma_f32 v30, v174, v50, v30
	v_fma_f32 v31, v175, v51, v31
	v_fma_f32 v30, v176, v56, v30
	v_fma_f32 v31, v177, v57, v31
	v_fma_f32 v30, v178, v54, v30
	v_fma_f32 v31, v179, v55, v31
	v_fma_f32 v30, v180, v60, v30
	v_fma_f32 v31, v181, v61, v31
	v_fma_f32 v30, v182, v58, v30
	v_fma_f32 v31, v183, v59, v31
	v_fma_f32 v30, v186, v64, v30
	v_fma_f32 v31, v187, v65, v31
	v_fma_f32 v30, v190, v62, v30
	v_fma_f32 v31, v191, v63, v31
	v_fma_f32 v210, v194, v68, v30
	v_fma_f32 v211, v195, v69, v31
	v_add_f32_e32 v30, v210, v211
	s_nop 1
	v_add_f32_dpp v30, v30, v30 quad_perm:[1,0,3,2] row_mask:0xf bank_mask:0xf
	s_nop 1
	v_add_f32_dpp v30, v30, v30 quad_perm:[2,3,0,1] row_mask:0xf bank_mask:0xf
	s_nop 1
	v_add_f32_dpp v30, v30, v30 row_half_mirror row_mask:0xf bank_mask:0xf
	s_nop 1
	v_add_f32_dpp v30, v30, v30 row_mirror row_mask:0xf bank_mask:0xf
	ds_bpermute_b32 v31, v242, v30
	s_waitcnt lgkmcnt(0)
	v_add_f32_e32 v30, v30, v31
	ds_bpermute_b32 v31, v243, v30
	s_and_saveexec_b64 s[0:1], s[2:3]
	s_cbranch_execz .LBB0_397
	s_add_i32 s4, s10, 0
	s_waitcnt lgkmcnt(0)
	v_add_f32_e32 v30, v30, v31
	v_mov_b32_e32 v31, s4
	ds_write_b32 v31, v30 offset:12
.LBB0_397:
	s_or_b64 exec, exec, s[0:1]
	v_fma_f32 v20, v188, v20, v198
	v_fma_f32 v21, v189, v21, v199
	v_fma_f32 v20, v130, v28, v20
	v_fma_f32 v21, v131, v29, v21
	v_fma_f32 v20, v132, v14, v20
	v_fma_f32 v21, v133, v15, v21
	v_fma_f32 v20, v134, v18, v20
	v_fma_f32 v21, v135, v19, v21
	v_fma_f32 v20, v136, v8, v20
	v_fma_f32 v21, v137, v9, v21
	v_fma_f32 v20, v138, v22, v20
	v_fma_f32 v21, v139, v23, v21
	v_fma_f32 v20, v140, v12, v20
	v_fma_f32 v21, v141, v13, v21
	v_fma_f32 v20, v142, v16, v20
	v_fma_f32 v21, v143, v17, v21
	v_fma_f32 v20, v144, v6, v20
	v_fma_f32 v21, v145, v7, v21
	v_fma_f32 v20, v146, v10, v20
	v_fma_f32 v21, v147, v11, v21
	v_fma_f32 v20, v148, v0, v20
	v_fma_f32 v21, v149, v1, v21
	v_fma_f32 v20, v150, v4, v20
	v_fma_f32 v21, v151, v5, v21
	v_fma_f32 v20, v152, v2, v20
	v_fma_f32 v21, v153, v3, v21
	v_fma_f32 v20, v154, v26, v20
	v_fma_f32 v21, v155, v27, v21
	v_fma_f32 v20, v156, v24, v20
	v_fma_f32 v21, v157, v25, v21
	v_fma_f32 v20, v158, v36, v20
	v_fma_f32 v21, v159, v37, v21
	v_fma_f32 v20, v160, v34, v20
	v_fma_f32 v21, v161, v35, v21
	v_fma_f32 v20, v162, v42, v20
	v_fma_f32 v21, v163, v43, v21
	v_fma_f32 v20, v164, v40, v20
	v_fma_f32 v21, v165, v41, v21
	v_fma_f32 v20, v166, v48, v20
	v_fma_f32 v21, v167, v49, v21
	v_fma_f32 v20, v168, v46, v20
	v_fma_f32 v21, v169, v47, v21
	v_fma_f32 v20, v170, v52, v20
	v_fma_f32 v21, v171, v53, v21
	v_fma_f32 v20, v172, v50, v20
	v_fma_f32 v21, v173, v51, v21
	v_fma_f32 v20, v174, v56, v20
	v_fma_f32 v21, v175, v57, v21
	v_fma_f32 v20, v176, v54, v20
	v_fma_f32 v21, v177, v55, v21
	v_fma_f32 v20, v178, v60, v20
	v_fma_f32 v21, v179, v61, v21
	v_fma_f32 v20, v180, v58, v20
	v_fma_f32 v21, v181, v59, v21
	v_fma_f32 v20, v182, v64, v20
	v_fma_f32 v21, v183, v65, v21
	v_fma_f32 v20, v186, v62, v20
	v_fma_f32 v21, v187, v63, v21
	v_fma_f32 v20, v190, v68, v20
	v_fma_f32 v21, v191, v69, v21
	v_fma_f32 v212, v194, v66, v20
	v_fma_f32 v213, v195, v67, v21
	v_add_f32_e32 v20, v212, v213
	s_nop 1
	v_add_f32_dpp v20, v20, v20 quad_perm:[1,0,3,2] row_mask:0xf bank_mask:0xf
	s_nop 1
	v_add_f32_dpp v20, v20, v20 quad_perm:[2,3,0,1] row_mask:0xf bank_mask:0xf
	s_nop 1
	v_add_f32_dpp v20, v20, v20 row_half_mirror row_mask:0xf bank_mask:0xf
	s_nop 1
	v_add_f32_dpp v20, v20, v20 row_mirror row_mask:0xf bank_mask:0xf
	ds_bpermute_b32 v21, v242, v20
	s_waitcnt lgkmcnt(0)
	v_add_f32_e32 v20, v20, v21
	ds_bpermute_b32 v21, v243, v20
	s_and_saveexec_b64 s[0:1], s[2:3]
	s_cbranch_execz .LBB0_399
	s_add_i32 s4, s10, 0
	s_waitcnt lgkmcnt(0)
	v_add_f32_e32 v20, v20, v21
	v_mov_b32_e32 v21, s4
	ds_write_b32 v21, v20 offset:16
; template <int PH>
; __device__ __forceinline__ void run_phase(const Args& args, LAS unsigned char* lds) {
;     ...
;                         for (int k = 0; k < 8; ++k) { const int i = 8 * ch + k; if (i < 46) { const int q = p0 - 15 + i; float u0 = 0.f, u1 = 0.f;
;                             if (q >= 0 && q < L) { u0 = bflo(ca[k]) * __builtin_amdgcn_rcpf(1.0f + __expf(-bflo(cgt[k]))); u1 = bfhi(ca[k]) * __builtin_amdgcn_rcpf(1.0f + __expf(-bfhi(cgt[k]))); }
; #pragma unroll
;                             for (int o = 0; o < 16; ++o) { const int kk = i - o; if (kk >= 0 && kk <= 30) { a0[o] += w0[kk] * u0; a1[o] += w1[kk] * u1; } } } }
; #pragma unroll
;                         for (int k = 0; k < 8; ++k) { ca[k] = na[k]; cgt[k] = ng[k]; }
;                     }
;     ...
;                     float mean[16], rstd[16];
; #pragma unroll
;                     for (int o = 0; o < 16; ++o) { const float s = wave_sum(a0[o] + a1[o]); if (lane == 0) red[wave * 16 + o] = s; }
.LBB0_399:
	s_or_b64 exec, exec, s[0:1]
	s_waitcnt lgkmcnt(0)
	v_fma_f32 v20, v188, v28, v198
	v_fma_f32 v21, v189, v29, v199
	v_fma_f32 v20, v130, v14, v20
	v_fma_f32 v21, v131, v15, v21
	v_fma_f32 v20, v132, v18, v20
	v_fma_f32 v21, v133, v19, v21
	v_fma_f32 v20, v134, v8, v20
	v_fma_f32 v21, v135, v9, v21
	v_fma_f32 v20, v136, v22, v20
	v_fma_f32 v21, v137, v23, v21
	v_fma_f32 v20, v138, v12, v20
	v_fma_f32 v21, v139, v13, v21
	v_fma_f32 v20, v140, v16, v20
	v_fma_f32 v21, v141, v17, v21
	v_fma_f32 v20, v142, v6, v20
	v_fma_f32 v21, v143, v7, v21
	v_fma_f32 v20, v144, v10, v20
	v_fma_f32 v21, v145, v11, v21
	v_fma_f32 v20, v146, v0, v20
	v_fma_f32 v21, v147, v1, v21
	v_fma_f32 v20, v148, v4, v20
	v_fma_f32 v21, v149, v5, v21
	v_fma_f32 v20, v150, v2, v20
	v_fma_f32 v21, v151, v3, v21
	v_fma_f32 v20, v152, v26, v20
	v_fma_f32 v21, v153, v27, v21
	v_fma_f32 v20, v154, v24, v20
	v_fma_f32 v21, v155, v25, v21
	v_fma_f32 v20, v156, v36, v20
	v_fma_f32 v21, v157, v37, v21
	v_fma_f32 v20, v158, v34, v20
	v_fma_f32 v21, v159, v35, v21
	v_fma_f32 v20, v160, v42, v20
	v_fma_f32 v21, v161, v43, v21
	v_fma_f32 v20, v162, v40, v20
	v_fma_f32 v21, v163, v41, v21
	v_fma_f32 v20, v164, v48, v20
	v_fma_f32 v21, v165, v49, v21
	v_fma_f32 v20, v166, v46, v20
	v_fma_f32 v21, v167, v47, v21
	v_fma_f32 v20, v168, v52, v20
	v_fma_f32 v21, v169, v53, v21
	v_fma_f32 v20, v170, v50, v20
	v_fma_f32 v21, v171, v51, v21
	v_fma_f32 v20, v172, v56, v20
	v_fma_f32 v21, v173, v57, v21
	v_fma_f32 v20, v174, v54, v20
	v_fma_f32 v21, v175, v55, v21
	v_fma_f32 v20, v176, v60, v20
	v_fma_f32 v21, v177, v61, v21
	v_fma_f32 v20, v178, v58, v20
	v_fma_f32 v21, v179, v59, v21
	v_fma_f32 v20, v180, v64, v20
	v_fma_f32 v21, v181, v65, v21
	v_fma_f32 v20, v182, v62, v20
	v_fma_f32 v21, v183, v63, v21
	v_fma_f32 v20, v186, v68, v20
	v_fma_f32 v21, v187, v69, v21
	v_fma_f32 v20, v190, v66, v20
	v_fma_f32 v21, v191, v67, v21
	v_fma_f32 v214, v194, v72, v20
	v_fma_f32 v215, v195, v73, v21
	v_add_f32_e32 v20, v214, v215
	s_nop 1
	v_add_f32_dpp v20, v20, v20 quad_perm:[1,0,3,2] row_mask:0xf bank_mask:0xf
	s_nop 1
	v_add_f32_dpp v20, v20, v20 quad_perm:[2,3,0,1] row_mask:0xf bank_mask:0xf
	s_nop 1
	v_add_f32_dpp v20, v20, v20 row_half_mirror row_mask:0xf bank_mask:0xf
	s_nop 1
	v_add_f32_dpp v20, v20, v20 row_mirror row_mask:0xf bank_mask:0xf
	ds_bpermute_b32 v21, v242, v20
	s_waitcnt lgkmcnt(0)
	v_add_f32_e32 v20, v20, v21
	ds_bpermute_b32 v21, v243, v20
	s_and_saveexec_b64 s[0:1], s[2:3]
	s_cbranch_execz .LBB0_401
	s_add_i32 s4, s10, 0
	s_waitcnt lgkmcnt(0)
	v_add_f32_e32 v20, v20, v21
	v_mov_b32_e32 v21, s4
	ds_write_b32 v21, v20 offset:20
.LBB0_401:
	s_or_b64 exec, exec, s[0:1]
	v_fma_f32 v14, v188, v14, v198
	v_fma_f32 v15, v189, v15, v199
	v_fma_f32 v14, v130, v18, v14
	v_fma_f32 v15, v131, v19, v15
	v_fma_f32 v14, v132, v8, v14
	v_fma_f32 v15, v133, v9, v15
	v_fma_f32 v14, v134, v22, v14
	v_fma_f32 v15, v135, v23, v15
	v_fma_f32 v14, v136, v12, v14
	v_fma_f32 v15, v137, v13, v15
	v_fma_f32 v14, v138, v16, v14
	v_fma_f32 v15, v139, v17, v15
	v_fma_f32 v14, v140, v6, v14
	v_fma_f32 v15, v141, v7, v15
	v_fma_f32 v14, v142, v10, v14
	v_fma_f32 v15, v143, v11, v15
	v_fma_f32 v14, v144, v0, v14
	v_fma_f32 v15, v145, v1, v15
	v_fma_f32 v14, v146, v4, v14
	v_fma_f32 v15, v147, v5, v15
	v_fma_f32 v14, v148, v2, v14
	v_fma_f32 v15, v149, v3, v15
	v_fma_f32 v14, v150, v26, v14
	v_fma_f32 v15, v151, v27, v15
	v_fma_f32 v14, v152, v24, v14
	v_fma_f32 v15, v153, v25, v15
	v_fma_f32 v14, v154, v36, v14
	v_fma_f32 v15, v155, v37, v15
	v_fma_f32 v14, v156, v34, v14
	v_fma_f32 v15, v157, v35, v15
	v_fma_f32 v14, v158, v42, v14
	v_fma_f32 v15, v159, v43, v15
	v_fma_f32 v14, v160, v40, v14
	v_fma_f32 v15, v161, v41, v15
	v_fma_f32 v14, v162, v48, v14
	v_fma_f32 v15, v163, v49, v15
	v_fma_f32 v14, v164, v46, v14
	v_fma_f32 v15, v165, v47, v15
	v_fma_f32 v14, v166, v52, v14
	v_fma_f32 v15, v167, v53, v15
	v_fma_f32 v14, v168, v50, v14
	v_fma_f32 v15, v169, v51, v15
	v_fma_f32 v14, v170, v56, v14
	v_fma_f32 v15, v171, v57, v15
	v_fma_f32 v14, v172, v54, v14
	v_fma_f32 v15, v173, v55, v15
	v_fma_f32 v14, v174, v60, v14
	v_fma_f32 v15, v175, v61, v15
	v_fma_f32 v14, v176, v58, v14
	v_fma_f32 v15, v177, v59, v15
	v_fma_f32 v14, v178, v64, v14
	v_fma_f32 v15, v179, v65, v15
	v_fma_f32 v14, v180, v62, v14
	v_fma_f32 v15, v181, v63, v15
	v_fma_f32 v14, v182, v68, v14
	v_fma_f32 v15, v183, v69, v15
	v_fma_f32 v14, v186, v66, v14
	v_fma_f32 v15, v187, v67, v15
	v_fma_f32 v14, v190, v72, v14
	v_fma_f32 v15, v191, v73, v15
	v_fma_f32 v216, v194, v70, v14
	v_fma_f32 v217, v195, v71, v15
	v_add_f32_e32 v14, v216, v217
	s_nop 1
	v_add_f32_dpp v14, v14, v14 quad_perm:[1,0,3,2] row_mask:0xf bank_mask:0xf
	s_nop 1
	v_add_f32_dpp v14, v14, v14 quad_perm:[2,3,0,1] row_mask:0xf bank_mask:0xf
	s_nop 1
	v_add_f32_dpp v14, v14, v14 row_half_mirror row_mask:0xf bank_mask:0xf
	s_nop 1
	v_add_f32_dpp v14, v14, v14 row_mirror row_mask:0xf bank_mask:0xf
	ds_bpermute_b32 v15, v242, v14
	s_waitcnt lgkmcnt(0)
	v_add_f32_e32 v14, v14, v15
	ds_bpermute_b32 v15, v243, v14
	s_and_saveexec_b64 s[0:1], s[2:3]
	s_cbranch_execz .LBB0_403
	s_add_i32 s4, s10, 0
	s_waitcnt lgkmcnt(0)
	v_add_f32_e32 v14, v14, v15
	v_mov_b32_e32 v15, s4
	ds_write_b32 v15, v14 offset:24
; template <int PH>
; __device__ __forceinline__ void run_phase(const Args& args, LAS unsigned char* lds) {
;     ...
;                         for (int k = 0; k < 8; ++k) { const int i = 8 * ch + k; if (i < 46) { const int q = p0 - 15 + i; float u0 = 0.f, u1 = 0.f;
;                             if (q >= 0 && q < L) { u0 = bflo(ca[k]) * __builtin_amdgcn_rcpf(1.0f + __expf(-bflo(cgt[k]))); u1 = bfhi(ca[k]) * __builtin_amdgcn_rcpf(1.0f + __expf(-bfhi(cgt[k]))); }
; #pragma unroll
;                             for (int o = 0; o < 16; ++o) { const int kk = i - o; if (kk >= 0 && kk <= 30) { a0[o] += w0[kk] * u0; a1[o] += w1[kk] * u1; } } } }
; #pragma unroll
;                         for (int k = 0; k < 8; ++k) { ca[k] = na[k]; cgt[k] = ng[k]; }
;                     }
;     ...
;                     float mean[16], rstd[16];
; #pragma unroll
;                     for (int o = 0; o < 16; ++o) { const float s = wave_sum(a0[o] + a1[o]); if (lane == 0) red[wave * 16 + o] = s; }
.LBB0_403:
	s_or_b64 exec, exec, s[0:1]
	s_waitcnt lgkmcnt(0)
	v_fma_f32 v14, v188, v18, v198
	v_fma_f32 v15, v189, v19, v199
	v_fma_f32 v14, v130, v8, v14
	v_fma_f32 v15, v131, v9, v15
	v_fma_f32 v14, v132, v22, v14
	v_fma_f32 v15, v133, v23, v15
	v_fma_f32 v14, v134, v12, v14
	v_fma_f32 v15, v135, v13, v15
	v_fma_f32 v14, v136, v16, v14
	v_fma_f32 v15, v137, v17, v15
	v_fma_f32 v14, v138, v6, v14
	v_fma_f32 v15, v139, v7, v15
	v_fma_f32 v14, v140, v10, v14
	v_fma_f32 v15, v141, v11, v15
	v_fma_f32 v14, v142, v0, v14
	v_fma_f32 v15, v143, v1, v15
	v_fma_f32 v14, v144, v4, v14
	v_fma_f32 v15, v145, v5, v15
	v_fma_f32 v14, v146, v2, v14
	v_fma_f32 v15, v147, v3, v15
	v_fma_f32 v14, v148, v26, v14
	v_fma_f32 v15, v149, v27, v15
	v_fma_f32 v14, v150, v24, v14
	v_fma_f32 v15, v151, v25, v15
	v_fma_f32 v14, v152, v36, v14
	v_fma_f32 v15, v153, v37, v15
	v_fma_f32 v14, v154, v34, v14
	v_fma_f32 v15, v155, v35, v15
	v_fma_f32 v14, v156, v42, v14
	v_fma_f32 v15, v157, v43, v15
	v_fma_f32 v14, v158, v40, v14
	v_fma_f32 v15, v159, v41, v15
	v_fma_f32 v14, v160, v48, v14
	v_fma_f32 v15, v161, v49, v15
	v_fma_f32 v14, v162, v46, v14
	v_fma_f32 v15, v163, v47, v15
	v_fma_f32 v14, v164, v52, v14
	v_fma_f32 v15, v165, v53, v15
	v_fma_f32 v14, v166, v50, v14
	v_fma_f32 v15, v167, v51, v15
	v_fma_f32 v14, v168, v56, v14
	v_fma_f32 v15, v169, v57, v15
	v_fma_f32 v14, v170, v54, v14
	v_fma_f32 v15, v171, v55, v15
	v_fma_f32 v14, v172, v60, v14
	v_fma_f32 v15, v173, v61, v15
	v_fma_f32 v14, v174, v58, v14
	v_fma_f32 v15, v175, v59, v15
	v_fma_f32 v14, v176, v64, v14
	v_fma_f32 v15, v177, v65, v15
	v_fma_f32 v14, v178, v62, v14
	v_fma_f32 v15, v179, v63, v15
	v_fma_f32 v14, v180, v68, v14
	v_fma_f32 v15, v181, v69, v15
	v_fma_f32 v14, v182, v66, v14
	v_fma_f32 v15, v183, v67, v15
	v_fma_f32 v14, v186, v72, v14
	v_fma_f32 v15, v187, v73, v15
	v_fma_f32 v14, v190, v70, v14
	v_fma_f32 v15, v191, v71, v15
	v_fma_f32 v218, v194, v76, v14
	v_fma_f32 v219, v195, v77, v15
	v_add_f32_e32 v14, v218, v219
	s_nop 1
	v_add_f32_dpp v14, v14, v14 quad_perm:[1,0,3,2] row_mask:0xf bank_mask:0xf
	s_nop 1
	v_add_f32_dpp v14, v14, v14 quad_perm:[2,3,0,1] row_mask:0xf bank_mask:0xf
	s_nop 1
	v_add_f32_dpp v14, v14, v14 row_half_mirror row_mask:0xf bank_mask:0xf
	s_nop 1
	v_add_f32_dpp v14, v14, v14 row_mirror row_mask:0xf bank_mask:0xf
	ds_bpermute_b32 v15, v242, v14
	s_waitcnt lgkmcnt(0)
	v_add_f32_e32 v14, v14, v15
	ds_bpermute_b32 v15, v243, v14
	s_and_saveexec_b64 s[0:1], s[2:3]
	s_cbranch_execz .LBB0_405
	s_add_i32 s4, s10, 0
	s_waitcnt lgkmcnt(0)
	v_add_f32_e32 v14, v14, v15
	v_mov_b32_e32 v15, s4
	ds_write_b32 v15, v14 offset:28
.LBB0_405:
	s_or_b64 exec, exec, s[0:1]
	v_fma_f32 v8, v188, v8, v198
	v_fma_f32 v9, v189, v9, v199
	v_fma_f32 v8, v130, v22, v8
	v_fma_f32 v9, v131, v23, v9
	v_fma_f32 v8, v132, v12, v8
	v_fma_f32 v9, v133, v13, v9
	v_fma_f32 v8, v134, v16, v8
	v_fma_f32 v9, v135, v17, v9
	v_fma_f32 v8, v136, v6, v8
	v_fma_f32 v9, v137, v7, v9
	v_fma_f32 v8, v138, v10, v8
	v_fma_f32 v9, v139, v11, v9
	v_fma_f32 v8, v140, v0, v8
	v_fma_f32 v9, v141, v1, v9
	v_fma_f32 v8, v142, v4, v8
	v_fma_f32 v9, v143, v5, v9
	v_fma_f32 v8, v144, v2, v8
	v_fma_f32 v9, v145, v3, v9
	v_fma_f32 v8, v146, v26, v8
	v_fma_f32 v9, v147, v27, v9
	v_fma_f32 v8, v148, v24, v8
	v_fma_f32 v9, v149, v25, v9
	v_fma_f32 v8, v150, v36, v8
	v_fma_f32 v9, v151, v37, v9
	v_fma_f32 v8, v152, v34, v8
	v_fma_f32 v9, v153, v35, v9
	v_fma_f32 v8, v154, v42, v8
	v_fma_f32 v9, v155, v43, v9
	v_fma_f32 v8, v156, v40, v8
	v_fma_f32 v9, v157, v41, v9
	v_fma_f32 v8, v158, v48, v8
	v_fma_f32 v9, v159, v49, v9
	v_fma_f32 v8, v160, v46, v8
	v_fma_f32 v9, v161, v47, v9
	v_fma_f32 v8, v162, v52, v8
	v_fma_f32 v9, v163, v53, v9
	v_fma_f32 v8, v164, v50, v8
	v_fma_f32 v9, v165, v51, v9
	v_fma_f32 v8, v166, v56, v8
	v_fma_f32 v9, v167, v57, v9
	v_fma_f32 v8, v168, v54, v8
	v_fma_f32 v9, v169, v55, v9
	v_fma_f32 v8, v170, v60, v8
	v_fma_f32 v9, v171, v61, v9
	v_fma_f32 v8, v172, v58, v8
	v_fma_f32 v9, v173, v59, v9
	v_fma_f32 v8, v174, v64, v8
	v_fma_f32 v9, v175, v65, v9
	v_fma_f32 v8, v176, v62, v8
	v_fma_f32 v9, v177, v63, v9
	v_fma_f32 v8, v178, v68, v8
	v_fma_f32 v9, v179, v69, v9
	v_fma_f32 v8, v180, v66, v8
	v_fma_f32 v9, v181, v67, v9
	v_fma_f32 v8, v182, v72, v8
	v_fma_f32 v9, v183, v73, v9
	v_fma_f32 v8, v186, v70, v8
	v_fma_f32 v9, v187, v71, v9
	v_fma_f32 v8, v190, v76, v8
	v_fma_f32 v9, v191, v77, v9
	v_fma_f32 v220, v194, v74, v8
	v_fma_f32 v221, v195, v75, v9
	v_add_f32_e32 v8, v220, v221
	s_nop 1
	v_add_f32_dpp v8, v8, v8 quad_perm:[1,0,3,2] row_mask:0xf bank_mask:0xf
	s_nop 1
	v_add_f32_dpp v8, v8, v8 quad_perm:[2,3,0,1] row_mask:0xf bank_mask:0xf
	s_nop 1
	v_add_f32_dpp v8, v8, v8 row_half_mirror row_mask:0xf bank_mask:0xf
	s_nop 1
	v_add_f32_dpp v8, v8, v8 row_mirror row_mask:0xf bank_mask:0xf
	ds_bpermute_b32 v9, v242, v8
	s_waitcnt lgkmcnt(0)
	v_add_f32_e32 v8, v8, v9
	ds_bpermute_b32 v9, v243, v8
	s_and_saveexec_b64 s[0:1], s[2:3]
	s_cbranch_execz .LBB0_407
	s_add_i32 s4, s10, 0
	s_waitcnt lgkmcnt(0)
	v_add_f32_e32 v8, v8, v9
	v_mov_b32_e32 v9, s4
	ds_write_b32 v9, v8 offset:32
; template <int PH>
; __device__ __forceinline__ void run_phase(const Args& args, LAS unsigned char* lds) {
;     ...
;                         for (int k = 0; k < 8; ++k) { const int i = 8 * ch + k; if (i < 46) { const int q = p0 - 15 + i; float u0 = 0.f, u1 = 0.f;
;                             if (q >= 0 && q < L) { u0 = bflo(ca[k]) * __builtin_amdgcn_rcpf(1.0f + __expf(-bflo(cgt[k]))); u1 = bfhi(ca[k]) * __builtin_amdgcn_rcpf(1.0f + __expf(-bfhi(cgt[k]))); }
; #pragma unroll
;                             for (int o = 0; o < 16; ++o) { const int kk = i - o; if (kk >= 0 && kk <= 30) { a0[o] += w0[kk] * u0; a1[o] += w1[kk] * u1; } } } }
; #pragma unroll
;                         for (int k = 0; k < 8; ++k) { ca[k] = na[k]; cgt[k] = ng[k]; }
;                     }
;     ...
;                     float mean[16], rstd[16];
; #pragma unroll
;                     for (int o = 0; o < 16; ++o) { const float s = wave_sum(a0[o] + a1[o]); if (lane == 0) red[wave * 16 + o] = s; }
.LBB0_407:
	s_or_b64 exec, exec, s[0:1]
	s_waitcnt lgkmcnt(0)
	v_fma_f32 v8, v188, v22, v198
	v_fma_f32 v9, v189, v23, v199
	v_fma_f32 v8, v130, v12, v8
	v_fma_f32 v9, v131, v13, v9
	v_fma_f32 v8, v132, v16, v8
	v_fma_f32 v9, v133, v17, v9
	v_fma_f32 v8, v134, v6, v8
	v_fma_f32 v9, v135, v7, v9
	v_fma_f32 v8, v136, v10, v8
	v_fma_f32 v9, v137, v11, v9
	v_fma_f32 v8, v138, v0, v8
	v_fma_f32 v9, v139, v1, v9
	v_fma_f32 v8, v140, v4, v8
	v_fma_f32 v9, v141, v5, v9
	v_fma_f32 v8, v142, v2, v8
	v_fma_f32 v9, v143, v3, v9
	v_fma_f32 v8, v144, v26, v8
	v_fma_f32 v9, v145, v27, v9
	v_fma_f32 v8, v146, v24, v8
	v_fma_f32 v9, v147, v25, v9
	v_fma_f32 v8, v148, v36, v8
	v_fma_f32 v9, v149, v37, v9
	v_fma_f32 v8, v150, v34, v8
	v_fma_f32 v9, v151, v35, v9
	v_fma_f32 v8, v152, v42, v8
	v_fma_f32 v9, v153, v43, v9
	v_fma_f32 v8, v154, v40, v8
	v_fma_f32 v9, v155, v41, v9
	v_fma_f32 v8, v156, v48, v8
	v_fma_f32 v9, v157, v49, v9
	v_fma_f32 v8, v158, v46, v8
	v_fma_f32 v9, v159, v47, v9
	v_fma_f32 v8, v160, v52, v8
	v_fma_f32 v9, v161, v53, v9
	v_fma_f32 v8, v162, v50, v8
	v_fma_f32 v9, v163, v51, v9
	v_fma_f32 v8, v164, v56, v8
	v_fma_f32 v9, v165, v57, v9
	v_fma_f32 v8, v166, v54, v8
	v_fma_f32 v9, v167, v55, v9
	v_fma_f32 v8, v168, v60, v8
	v_fma_f32 v9, v169, v61, v9
	v_fma_f32 v8, v170, v58, v8
	v_fma_f32 v9, v171, v59, v9
	v_fma_f32 v8, v172, v64, v8
	v_fma_f32 v9, v173, v65, v9
	v_fma_f32 v8, v174, v62, v8
	v_fma_f32 v9, v175, v63, v9
	v_fma_f32 v8, v176, v68, v8
	v_fma_f32 v9, v177, v69, v9
	v_fma_f32 v8, v178, v66, v8
	v_fma_f32 v9, v179, v67, v9
	v_fma_f32 v8, v180, v72, v8
	v_fma_f32 v9, v181, v73, v9
	v_fma_f32 v8, v182, v70, v8
	v_fma_f32 v9, v183, v71, v9
	v_fma_f32 v8, v186, v76, v8
	v_fma_f32 v9, v187, v77, v9
	v_fma_f32 v8, v190, v74, v8
	v_fma_f32 v9, v191, v75, v9
	v_fma_f32 v222, v194, v80, v8
	v_fma_f32 v223, v195, v81, v9
	v_add_f32_e32 v8, v222, v223
	s_nop 1
	v_add_f32_dpp v8, v8, v8 quad_perm:[1,0,3,2] row_mask:0xf bank_mask:0xf
	s_nop 1
	v_add_f32_dpp v8, v8, v8 quad_perm:[2,3,0,1] row_mask:0xf bank_mask:0xf
	s_nop 1
	v_add_f32_dpp v8, v8, v8 row_half_mirror row_mask:0xf bank_mask:0xf
	s_nop 1
	v_add_f32_dpp v8, v8, v8 row_mirror row_mask:0xf bank_mask:0xf
	ds_bpermute_b32 v9, v242, v8
	s_waitcnt lgkmcnt(0)
	v_add_f32_e32 v8, v8, v9
	ds_bpermute_b32 v9, v243, v8
	s_and_saveexec_b64 s[0:1], s[2:3]
	s_cbranch_execz .LBB0_409
	s_add_i32 s4, s10, 0
	s_waitcnt lgkmcnt(0)
	v_add_f32_e32 v8, v8, v9
	v_mov_b32_e32 v9, s4
	ds_write_b32 v9, v8 offset:36
.LBB0_409:
	s_or_b64 exec, exec, s[0:1]
	s_waitcnt lgkmcnt(0)
	v_fma_f32 v8, v188, v12, v198
	v_fma_f32 v9, v189, v13, v199
	v_fma_f32 v8, v130, v16, v8
	v_fma_f32 v9, v131, v17, v9
	v_fma_f32 v8, v132, v6, v8
	v_fma_f32 v9, v133, v7, v9
	v_fma_f32 v8, v134, v10, v8
	v_fma_f32 v9, v135, v11, v9
	v_fma_f32 v8, v136, v0, v8
	v_fma_f32 v9, v137, v1, v9
	v_fma_f32 v8, v138, v4, v8
	v_fma_f32 v9, v139, v5, v9
	v_fma_f32 v8, v140, v2, v8
	v_fma_f32 v9, v141, v3, v9
	v_fma_f32 v8, v142, v26, v8
	v_fma_f32 v9, v143, v27, v9
	v_fma_f32 v8, v144, v24, v8
	v_fma_f32 v9, v145, v25, v9
	v_fma_f32 v8, v146, v36, v8
	v_fma_f32 v9, v147, v37, v9
	v_fma_f32 v8, v148, v34, v8
	v_fma_f32 v9, v149, v35, v9
	v_fma_f32 v8, v150, v42, v8
	v_fma_f32 v9, v151, v43, v9
	v_fma_f32 v8, v152, v40, v8
	v_fma_f32 v9, v153, v41, v9
	v_fma_f32 v8, v154, v48, v8
	v_fma_f32 v9, v155, v49, v9
	v_fma_f32 v8, v156, v46, v8
	v_fma_f32 v9, v157, v47, v9
	v_fma_f32 v8, v158, v52, v8
	v_fma_f32 v9, v159, v53, v9
	v_fma_f32 v8, v160, v50, v8
	v_fma_f32 v9, v161, v51, v9
	v_fma_f32 v8, v162, v56, v8
	v_fma_f32 v9, v163, v57, v9
	v_fma_f32 v8, v164, v54, v8
	v_fma_f32 v9, v165, v55, v9
	v_fma_f32 v8, v166, v60, v8
	v_fma_f32 v9, v167, v61, v9
	v_fma_f32 v8, v168, v58, v8
	v_fma_f32 v9, v169, v59, v9
	v_fma_f32 v8, v170, v64, v8
	v_fma_f32 v9, v171, v65, v9
	v_fma_f32 v8, v172, v62, v8
	v_fma_f32 v9, v173, v63, v9
	v_fma_f32 v8, v174, v68, v8
	v_fma_f32 v9, v175, v69, v9
	v_fma_f32 v8, v176, v66, v8
	v_fma_f32 v9, v177, v67, v9
	v_fma_f32 v8, v178, v72, v8
	v_fma_f32 v9, v179, v73, v9
	v_fma_f32 v8, v180, v70, v8
	v_fma_f32 v9, v181, v71, v9
	v_fma_f32 v8, v182, v76, v8
	v_fma_f32 v9, v183, v77, v9
	v_fma_f32 v8, v186, v74, v8
	v_fma_f32 v9, v187, v75, v9
	v_fma_f32 v8, v190, v80, v8
	v_fma_f32 v9, v191, v81, v9
	v_fma_f32 v224, v194, v78, v8
	v_fma_f32 v225, v195, v79, v9
	v_add_f32_e32 v8, v224, v225
	s_nop 1
	v_add_f32_dpp v8, v8, v8 quad_perm:[1,0,3,2] row_mask:0xf bank_mask:0xf
	s_nop 1
	v_add_f32_dpp v8, v8, v8 quad_perm:[2,3,0,1] row_mask:0xf bank_mask:0xf
	s_nop 1
	v_add_f32_dpp v8, v8, v8 row_half_mirror row_mask:0xf bank_mask:0xf
	s_nop 1
	v_add_f32_dpp v8, v8, v8 row_mirror row_mask:0xf bank_mask:0xf
	ds_bpermute_b32 v9, v242, v8
	s_waitcnt lgkmcnt(0)
	v_add_f32_e32 v8, v8, v9
	ds_bpermute_b32 v9, v243, v8
	s_and_saveexec_b64 s[0:1], s[2:3]
	s_cbranch_execz .LBB0_411
	s_add_i32 s4, s10, 0
	s_waitcnt lgkmcnt(0)
	v_add_f32_e32 v8, v8, v9
	v_mov_b32_e32 v9, s4
	ds_write_b32 v9, v8 offset:40
; template <int PH>
; __device__ __forceinline__ void run_phase(const Args& args, LAS unsigned char* lds) {
;     ...
;                         for (int k = 0; k < 8; ++k) { const int i = 8 * ch + k; if (i < 46) { const int q = p0 - 15 + i; float u0 = 0.f, u1 = 0.f;
;                             if (q >= 0 && q < L) { u0 = bflo(ca[k]) * __builtin_amdgcn_rcpf(1.0f + __expf(-bflo(cgt[k]))); u1 = bfhi(ca[k]) * __builtin_amdgcn_rcpf(1.0f + __expf(-bfhi(cgt[k]))); }
; #pragma unroll
;                             for (int o = 0; o < 16; ++o) { const int kk = i - o; if (kk >= 0 && kk <= 30) { a0[o] += w0[kk] * u0; a1[o] += w1[kk] * u1; } } } }
; #pragma unroll
;                         for (int k = 0; k < 8; ++k) { ca[k] = na[k]; cgt[k] = ng[k]; }
;                     }
;     ...
;                     float mean[16], rstd[16];
; #pragma unroll
;                     for (int o = 0; o < 16; ++o) { const float s = wave_sum(a0[o] + a1[o]); if (lane == 0) red[wave * 16 + o] = s; }
.LBB0_411:
	s_or_b64 exec, exec, s[0:1]
	s_waitcnt lgkmcnt(0)
	v_fma_f32 v8, v188, v16, v198
	v_fma_f32 v9, v189, v17, v199
	v_fma_f32 v8, v130, v6, v8
	v_fma_f32 v9, v131, v7, v9
	v_fma_f32 v8, v132, v10, v8
	v_fma_f32 v9, v133, v11, v9
	v_fma_f32 v8, v134, v0, v8
	v_fma_f32 v9, v135, v1, v9
	v_fma_f32 v8, v136, v4, v8
	v_fma_f32 v9, v137, v5, v9
	v_fma_f32 v8, v138, v2, v8
	v_fma_f32 v9, v139, v3, v9
	v_fma_f32 v8, v140, v26, v8
	v_fma_f32 v9, v141, v27, v9
	v_fma_f32 v8, v142, v24, v8
	v_fma_f32 v9, v143, v25, v9
	v_fma_f32 v8, v144, v36, v8
	v_fma_f32 v9, v145, v37, v9
	v_fma_f32 v8, v146, v34, v8
	v_fma_f32 v9, v147, v35, v9
	v_fma_f32 v8, v148, v42, v8
	v_fma_f32 v9, v149, v43, v9
	v_fma_f32 v8, v150, v40, v8
	v_fma_f32 v9, v151, v41, v9
	v_fma_f32 v8, v152, v48, v8
	v_fma_f32 v9, v153, v49, v9
	v_fma_f32 v8, v154, v46, v8
	v_fma_f32 v9, v155, v47, v9
	v_fma_f32 v8, v156, v52, v8
	v_fma_f32 v9, v157, v53, v9
	v_fma_f32 v8, v158, v50, v8
	v_fma_f32 v9, v159, v51, v9
	v_fma_f32 v8, v160, v56, v8
	v_fma_f32 v9, v161, v57, v9
	v_fma_f32 v8, v162, v54, v8
	v_fma_f32 v9, v163, v55, v9
	v_fma_f32 v8, v164, v60, v8
	v_fma_f32 v9, v165, v61, v9
	v_fma_f32 v8, v166, v58, v8
	v_fma_f32 v9, v167, v59, v9
	v_fma_f32 v8, v168, v64, v8
	v_fma_f32 v9, v169, v65, v9
	v_fma_f32 v8, v170, v62, v8
	v_fma_f32 v9, v171, v63, v9
	v_fma_f32 v8, v172, v68, v8
	v_fma_f32 v9, v173, v69, v9
	v_fma_f32 v8, v174, v66, v8
	v_fma_f32 v9, v175, v67, v9
	v_fma_f32 v8, v176, v72, v8
	v_fma_f32 v9, v177, v73, v9
	v_fma_f32 v8, v178, v70, v8
	v_fma_f32 v9, v179, v71, v9
	v_fma_f32 v8, v180, v76, v8
	v_fma_f32 v9, v181, v77, v9
	v_fma_f32 v8, v182, v74, v8
	v_fma_f32 v9, v183, v75, v9
	v_fma_f32 v8, v186, v80, v8
	v_fma_f32 v9, v187, v81, v9
	v_fma_f32 v8, v190, v78, v8
	v_fma_f32 v9, v191, v79, v9
	v_fma_f32 v226, v194, v84, v8
	v_fma_f32 v227, v195, v85, v9
	v_add_f32_e32 v8, v226, v227
	s_nop 1
	v_add_f32_dpp v8, v8, v8 quad_perm:[1,0,3,2] row_mask:0xf bank_mask:0xf
	s_nop 1
	v_add_f32_dpp v8, v8, v8 quad_perm:[2,3,0,1] row_mask:0xf bank_mask:0xf
	s_nop 1
	v_add_f32_dpp v8, v8, v8 row_half_mirror row_mask:0xf bank_mask:0xf
	s_nop 1
	v_add_f32_dpp v8, v8, v8 row_mirror row_mask:0xf bank_mask:0xf
	ds_bpermute_b32 v9, v242, v8
	s_waitcnt lgkmcnt(0)
	v_add_f32_e32 v8, v8, v9
	ds_bpermute_b32 v9, v243, v8
	s_and_saveexec_b64 s[0:1], s[2:3]
	s_cbranch_execz .LBB0_413
	s_add_i32 s4, s10, 0
	s_waitcnt lgkmcnt(0)
	v_add_f32_e32 v8, v8, v9
	v_mov_b32_e32 v9, s4
	ds_write_b32 v9, v8 offset:44
.LBB0_413:
	s_or_b64 exec, exec, s[0:1]
	v_fma_f32 v6, v188, v6, v198
	v_fma_f32 v7, v189, v7, v199
	v_fma_f32 v6, v130, v10, v6
	v_fma_f32 v7, v131, v11, v7
	v_fma_f32 v6, v132, v0, v6
	v_fma_f32 v7, v133, v1, v7
	v_fma_f32 v6, v134, v4, v6
	v_fma_f32 v7, v135, v5, v7
	v_fma_f32 v6, v136, v2, v6
	v_fma_f32 v7, v137, v3, v7
	v_fma_f32 v6, v138, v26, v6
	v_fma_f32 v7, v139, v27, v7
	v_fma_f32 v6, v140, v24, v6
	v_fma_f32 v7, v141, v25, v7
	v_fma_f32 v6, v142, v36, v6
	v_fma_f32 v7, v143, v37, v7
	v_fma_f32 v6, v144, v34, v6
	v_fma_f32 v7, v145, v35, v7
	v_fma_f32 v6, v146, v42, v6
	v_fma_f32 v7, v147, v43, v7
	v_fma_f32 v6, v148, v40, v6
	v_fma_f32 v7, v149, v41, v7
	v_fma_f32 v6, v150, v48, v6
	v_fma_f32 v7, v151, v49, v7
	v_fma_f32 v6, v152, v46, v6
	v_fma_f32 v7, v153, v47, v7
	v_fma_f32 v6, v154, v52, v6
	v_fma_f32 v7, v155, v53, v7
	v_fma_f32 v6, v156, v50, v6
	v_fma_f32 v7, v157, v51, v7
	v_fma_f32 v6, v158, v56, v6
	v_fma_f32 v7, v159, v57, v7
	v_fma_f32 v6, v160, v54, v6
	v_fma_f32 v7, v161, v55, v7
	v_fma_f32 v6, v162, v60, v6
	v_fma_f32 v7, v163, v61, v7
	v_fma_f32 v6, v164, v58, v6
	v_fma_f32 v7, v165, v59, v7
	v_fma_f32 v6, v166, v64, v6
	v_fma_f32 v7, v167, v65, v7
	v_fma_f32 v6, v168, v62, v6
	v_fma_f32 v7, v169, v63, v7
	v_fma_f32 v6, v170, v68, v6
	v_fma_f32 v7, v171, v69, v7
	v_fma_f32 v6, v172, v66, v6
	v_fma_f32 v7, v173, v67, v7
	v_fma_f32 v6, v174, v72, v6
	v_fma_f32 v7, v175, v73, v7
	v_fma_f32 v6, v176, v70, v6
	v_fma_f32 v7, v177, v71, v7
	v_fma_f32 v6, v178, v76, v6
	v_fma_f32 v7, v179, v77, v7
	v_fma_f32 v6, v180, v74, v6
	v_fma_f32 v7, v181, v75, v7
	v_fma_f32 v6, v182, v80, v6
	v_fma_f32 v7, v183, v81, v7
	v_fma_f32 v6, v186, v78, v6
	v_fma_f32 v7, v187, v79, v7
	v_fma_f32 v6, v190, v84, v6
	v_fma_f32 v7, v191, v85, v7
	v_fma_f32 v228, v194, v82, v6
	v_fma_f32 v229, v195, v83, v7
	v_add_f32_e32 v6, v228, v229
	s_nop 1
	v_add_f32_dpp v6, v6, v6 quad_perm:[1,0,3,2] row_mask:0xf bank_mask:0xf
	s_nop 1
	v_add_f32_dpp v6, v6, v6 quad_perm:[2,3,0,1] row_mask:0xf bank_mask:0xf
	s_nop 1
	v_add_f32_dpp v6, v6, v6 row_half_mirror row_mask:0xf bank_mask:0xf
	s_nop 1
	v_add_f32_dpp v6, v6, v6 row_mirror row_mask:0xf bank_mask:0xf
	ds_bpermute_b32 v7, v242, v6
	s_waitcnt lgkmcnt(0)
	v_add_f32_e32 v6, v6, v7
	ds_bpermute_b32 v7, v243, v6
	s_and_saveexec_b64 s[0:1], s[2:3]
	s_cbranch_execz .LBB0_415
	s_add_i32 s4, s10, 0
	s_waitcnt lgkmcnt(0)
	v_add_f32_e32 v6, v6, v7
	v_mov_b32_e32 v7, s4
	ds_write_b32 v7, v6 offset:48
; template <int PH>
; __device__ __forceinline__ void run_phase(const Args& args, LAS unsigned char* lds) {
;     ...
;                         for (int k = 0; k < 8; ++k) { const int i = 8 * ch + k; if (i < 46) { const int q = p0 - 15 + i; float u0 = 0.f, u1 = 0.f;
;                             if (q >= 0 && q < L) { u0 = bflo(ca[k]) * __builtin_amdgcn_rcpf(1.0f + __expf(-bflo(cgt[k]))); u1 = bfhi(ca[k]) * __builtin_amdgcn_rcpf(1.0f + __expf(-bfhi(cgt[k]))); }
; #pragma unroll
;                             for (int o = 0; o < 16; ++o) { const int kk = i - o; if (kk >= 0 && kk <= 30) { a0[o] += w0[kk] * u0; a1[o] += w1[kk] * u1; } } } }
; #pragma unroll
;                         for (int k = 0; k < 8; ++k) { ca[k] = na[k]; cgt[k] = ng[k]; }
;                     }
;     ...
;                     float mean[16], rstd[16];
; #pragma unroll
;                     for (int o = 0; o < 16; ++o) { const float s = wave_sum(a0[o] + a1[o]); if (lane == 0) red[wave * 16 + o] = s; }
.LBB0_415:
	s_or_b64 exec, exec, s[0:1]
	s_waitcnt lgkmcnt(0)
	v_fma_f32 v6, v188, v10, v198
	v_fma_f32 v7, v189, v11, v199
	v_fma_f32 v6, v130, v0, v6
	v_fma_f32 v7, v131, v1, v7
	v_fma_f32 v6, v132, v4, v6
	v_fma_f32 v7, v133, v5, v7
	v_fma_f32 v6, v134, v2, v6
	v_fma_f32 v7, v135, v3, v7
	v_fma_f32 v6, v136, v26, v6
	v_fma_f32 v7, v137, v27, v7
	v_fma_f32 v6, v138, v24, v6
	v_fma_f32 v7, v139, v25, v7
	v_fma_f32 v6, v140, v36, v6
	v_fma_f32 v7, v141, v37, v7
	v_fma_f32 v6, v142, v34, v6
	v_fma_f32 v7, v143, v35, v7
	v_fma_f32 v6, v144, v42, v6
	v_fma_f32 v7, v145, v43, v7
	v_fma_f32 v6, v146, v40, v6
	v_fma_f32 v7, v147, v41, v7
	v_fma_f32 v6, v148, v48, v6
	v_fma_f32 v7, v149, v49, v7
	v_fma_f32 v6, v150, v46, v6
	v_fma_f32 v7, v151, v47, v7
	v_fma_f32 v6, v152, v52, v6
	v_fma_f32 v7, v153, v53, v7
	v_fma_f32 v6, v154, v50, v6
	v_fma_f32 v7, v155, v51, v7
	v_fma_f32 v6, v156, v56, v6
	v_fma_f32 v7, v157, v57, v7
	v_fma_f32 v6, v158, v54, v6
	v_fma_f32 v7, v159, v55, v7
	v_fma_f32 v6, v160, v60, v6
	v_fma_f32 v7, v161, v61, v7
	v_fma_f32 v6, v162, v58, v6
	v_fma_f32 v7, v163, v59, v7
	v_fma_f32 v6, v164, v64, v6
	v_fma_f32 v7, v165, v65, v7
	v_fma_f32 v6, v166, v62, v6
	v_fma_f32 v7, v167, v63, v7
	v_fma_f32 v6, v168, v68, v6
	v_fma_f32 v7, v169, v69, v7
	v_fma_f32 v6, v170, v66, v6
	v_fma_f32 v7, v171, v67, v7
	v_fma_f32 v6, v172, v72, v6
	v_fma_f32 v7, v173, v73, v7
	v_fma_f32 v6, v174, v70, v6
	v_fma_f32 v7, v175, v71, v7
	v_fma_f32 v6, v176, v76, v6
	v_fma_f32 v7, v177, v77, v7
	v_fma_f32 v6, v178, v74, v6
	v_fma_f32 v7, v179, v75, v7
	v_fma_f32 v6, v180, v80, v6
	v_fma_f32 v7, v181, v81, v7
	v_fma_f32 v6, v182, v78, v6
	v_fma_f32 v7, v183, v79, v7
	v_fma_f32 v6, v186, v84, v6
	v_fma_f32 v7, v187, v85, v7
	v_fma_f32 v6, v190, v82, v6
	v_fma_f32 v7, v191, v83, v7
	v_fma_f32 v230, v194, v88, v6
	v_fma_f32 v231, v195, v89, v7
	v_add_f32_e32 v6, v230, v231
	s_nop 1
	v_add_f32_dpp v6, v6, v6 quad_perm:[1,0,3,2] row_mask:0xf bank_mask:0xf
	s_nop 1
	v_add_f32_dpp v6, v6, v6 quad_perm:[2,3,0,1] row_mask:0xf bank_mask:0xf
	s_nop 1
	v_add_f32_dpp v6, v6, v6 row_half_mirror row_mask:0xf bank_mask:0xf
	s_nop 1
	v_add_f32_dpp v6, v6, v6 row_mirror row_mask:0xf bank_mask:0xf
	ds_bpermute_b32 v7, v242, v6
	s_waitcnt lgkmcnt(0)
	v_add_f32_e32 v6, v6, v7
	ds_bpermute_b32 v7, v243, v6
	s_and_saveexec_b64 s[0:1], s[2:3]
	s_cbranch_execz .LBB0_417
	s_add_i32 s4, s10, 0
	s_waitcnt lgkmcnt(0)
	v_add_f32_e32 v6, v6, v7
	v_mov_b32_e32 v7, s4
	ds_write_b32 v7, v6 offset:52
.LBB0_417:
	s_or_b64 exec, exec, s[0:1]
	v_fma_f32 v0, v188, v0, v198
	v_fma_f32 v1, v189, v1, v199
	v_fma_f32 v0, v130, v4, v0
	v_fma_f32 v1, v131, v5, v1
	v_fma_f32 v0, v132, v2, v0
	v_fma_f32 v1, v133, v3, v1
	v_fma_f32 v0, v134, v26, v0
	v_fma_f32 v1, v135, v27, v1
	v_fma_f32 v0, v136, v24, v0
	v_fma_f32 v1, v137, v25, v1
	v_fma_f32 v0, v138, v36, v0
	v_fma_f32 v1, v139, v37, v1
	v_fma_f32 v0, v140, v34, v0
	v_fma_f32 v1, v141, v35, v1
	v_fma_f32 v0, v142, v42, v0
	v_fma_f32 v1, v143, v43, v1
	v_fma_f32 v0, v144, v40, v0
	v_fma_f32 v1, v145, v41, v1
	v_fma_f32 v0, v146, v48, v0
	v_fma_f32 v1, v147, v49, v1
	v_fma_f32 v0, v148, v46, v0
	v_fma_f32 v1, v149, v47, v1
	v_fma_f32 v0, v150, v52, v0
	v_fma_f32 v1, v151, v53, v1
	v_fma_f32 v0, v152, v50, v0
	v_fma_f32 v1, v153, v51, v1
	v_fma_f32 v0, v154, v56, v0
	v_fma_f32 v1, v155, v57, v1
	v_fma_f32 v0, v156, v54, v0
	v_fma_f32 v1, v157, v55, v1
	v_fma_f32 v0, v158, v60, v0
	v_fma_f32 v1, v159, v61, v1
	v_fma_f32 v0, v160, v58, v0
	v_fma_f32 v1, v161, v59, v1
	v_fma_f32 v0, v162, v64, v0
	v_fma_f32 v1, v163, v65, v1
	v_fma_f32 v0, v164, v62, v0
	v_fma_f32 v1, v165, v63, v1
	v_fma_f32 v0, v166, v68, v0
	v_fma_f32 v1, v167, v69, v1
	v_fma_f32 v0, v168, v66, v0
	v_fma_f32 v1, v169, v67, v1
	v_fma_f32 v0, v170, v72, v0
	v_fma_f32 v1, v171, v73, v1
	v_fma_f32 v0, v172, v70, v0
	v_fma_f32 v1, v173, v71, v1
	v_fma_f32 v0, v174, v76, v0
	v_fma_f32 v1, v175, v77, v1
	v_fma_f32 v0, v176, v74, v0
	v_fma_f32 v1, v177, v75, v1
	v_fma_f32 v0, v178, v80, v0
	v_fma_f32 v1, v179, v81, v1
	v_fma_f32 v0, v180, v78, v0
	v_fma_f32 v1, v181, v79, v1
	v_fma_f32 v0, v182, v84, v0
	v_fma_f32 v1, v183, v85, v1
	v_fma_f32 v0, v186, v82, v0
	v_fma_f32 v1, v187, v83, v1
	v_fma_f32 v0, v190, v88, v0
	v_fma_f32 v1, v191, v89, v1
	v_fma_f32 v232, v194, v86, v0
	v_fma_f32 v233, v195, v87, v1
	v_add_f32_e32 v0, v232, v233
	s_nop 1
	v_add_f32_dpp v0, v0, v0 quad_perm:[1,0,3,2] row_mask:0xf bank_mask:0xf
	s_nop 1
	v_add_f32_dpp v0, v0, v0 quad_perm:[2,3,0,1] row_mask:0xf bank_mask:0xf
	s_nop 1
	v_add_f32_dpp v0, v0, v0 row_half_mirror row_mask:0xf bank_mask:0xf
	s_nop 1
	v_add_f32_dpp v0, v0, v0 row_mirror row_mask:0xf bank_mask:0xf
	ds_bpermute_b32 v1, v242, v0
	s_waitcnt lgkmcnt(0)
	v_add_f32_e32 v0, v0, v1
	ds_bpermute_b32 v1, v243, v0
	s_and_saveexec_b64 s[0:1], s[2:3]
	s_cbranch_execz .LBB0_419
	s_add_i32 s4, s10, 0
	s_waitcnt lgkmcnt(0)
	v_add_f32_e32 v0, v0, v1
	v_mov_b32_e32 v1, s4
	ds_write_b32 v1, v0 offset:56
; template <int PH>
; __device__ __forceinline__ void run_phase(const Args& args, LAS unsigned char* lds) {
;     ...
;                         for (int k = 0; k < 8; ++k) { const int i = 8 * ch + k; if (i < 46) { const int q = p0 - 15 + i; float u0 = 0.f, u1 = 0.f;
;                             if (q >= 0 && q < L) { u0 = bflo(ca[k]) * __builtin_amdgcn_rcpf(1.0f + __expf(-bflo(cgt[k]))); u1 = bfhi(ca[k]) * __builtin_amdgcn_rcpf(1.0f + __expf(-bfhi(cgt[k]))); }
; #pragma unroll
;                             for (int o = 0; o < 16; ++o) { const int kk = i - o; if (kk >= 0 && kk <= 30) { a0[o] += w0[kk] * u0; a1[o] += w1[kk] * u1; } } } }
; #pragma unroll
;                         for (int k = 0; k < 8; ++k) { ca[k] = na[k]; cgt[k] = ng[k]; }
;                     }
;     ...
;                     float mean[16], rstd[16];
; #pragma unroll
;                     for (int o = 0; o < 16; ++o) { const float s = wave_sum(a0[o] + a1[o]); if (lane == 0) red[wave * 16 + o] = s; }
.LBB0_419:
	s_or_b64 exec, exec, s[0:1]
	s_waitcnt lgkmcnt(0)
	v_fma_f32 v0, v188, v4, v198
	v_fma_f32 v1, v189, v5, v199
	v_fma_f32 v0, v130, v2, v0
	v_fma_f32 v1, v131, v3, v1
	v_fma_f32 v0, v132, v26, v0
	v_fma_f32 v1, v133, v27, v1
	v_fma_f32 v0, v134, v24, v0
	v_fma_f32 v1, v135, v25, v1
	v_fma_f32 v0, v136, v36, v0
	v_fma_f32 v1, v137, v37, v1
	v_fma_f32 v0, v138, v34, v0
	v_fma_f32 v1, v139, v35, v1
	v_fma_f32 v0, v140, v42, v0
	v_fma_f32 v1, v141, v43, v1
	v_fma_f32 v0, v142, v40, v0
	v_fma_f32 v1, v143, v41, v1
	v_fma_f32 v0, v144, v48, v0
	v_fma_f32 v1, v145, v49, v1
	v_fma_f32 v0, v146, v46, v0
	v_fma_f32 v1, v147, v47, v1
	v_fma_f32 v0, v148, v52, v0
	v_fma_f32 v1, v149, v53, v1
	v_fma_f32 v0, v150, v50, v0
	v_fma_f32 v1, v151, v51, v1
	v_fma_f32 v0, v152, v56, v0
	v_fma_f32 v1, v153, v57, v1
	v_fma_f32 v0, v154, v54, v0
	v_fma_f32 v1, v155, v55, v1
	v_fma_f32 v0, v156, v60, v0
	v_fma_f32 v1, v157, v61, v1
	v_fma_f32 v0, v158, v58, v0
	v_fma_f32 v1, v159, v59, v1
	v_fma_f32 v0, v160, v64, v0
	v_fma_f32 v1, v161, v65, v1
	v_fma_f32 v0, v162, v62, v0
	v_fma_f32 v1, v163, v63, v1
	v_fma_f32 v0, v164, v68, v0
	v_fma_f32 v1, v165, v69, v1
	v_fma_f32 v0, v166, v66, v0
	v_fma_f32 v1, v167, v67, v1
	v_fma_f32 v0, v168, v72, v0
	v_fma_f32 v1, v169, v73, v1
	v_fma_f32 v0, v170, v70, v0
	v_fma_f32 v1, v171, v71, v1
	v_fma_f32 v0, v172, v76, v0
	v_fma_f32 v1, v173, v77, v1
	v_fma_f32 v0, v174, v74, v0
	v_fma_f32 v1, v175, v75, v1
	v_fma_f32 v0, v176, v80, v0
	v_fma_f32 v1, v177, v81, v1
	v_fma_f32 v0, v178, v78, v0
	v_fma_f32 v1, v179, v79, v1
	v_fma_f32 v0, v180, v84, v0
	v_fma_f32 v1, v181, v85, v1
	v_fma_f32 v0, v182, v82, v0
	v_fma_f32 v1, v183, v83, v1
	v_fma_f32 v0, v186, v88, v0
	v_fma_f32 v1, v187, v89, v1
	v_fma_f32 v0, v190, v86, v0
	v_fma_f32 v1, v191, v87, v1
	v_fma_f32 v234, v194, v90, v0
	v_fma_f32 v235, v195, v91, v1
	v_add_f32_e32 v0, v234, v235
	s_nop 1
	v_add_f32_dpp v0, v0, v0 quad_perm:[1,0,3,2] row_mask:0xf bank_mask:0xf
	s_nop 1
	v_add_f32_dpp v0, v0, v0 quad_perm:[2,3,0,1] row_mask:0xf bank_mask:0xf
	s_nop 1
	v_add_f32_dpp v0, v0, v0 row_half_mirror row_mask:0xf bank_mask:0xf
	s_nop 1
	v_add_f32_dpp v0, v0, v0 row_mirror row_mask:0xf bank_mask:0xf
	ds_bpermute_b32 v1, v242, v0
	s_waitcnt lgkmcnt(0)
	v_add_f32_e32 v0, v0, v1
	ds_bpermute_b32 v1, v243, v0
	s_and_saveexec_b64 s[0:1], s[2:3]
	s_cbranch_execz .LBB0_421
	s_add_i32 s4, s10, 0
	s_waitcnt lgkmcnt(0)
	v_add_f32_e32 v0, v0, v1
	v_mov_b32_e32 v1, s4
	ds_write_b32 v1, v0 offset:60

; template <int PH>
; __device__ __forceinline__ void run_phase(const Args& args, LAS unsigned char* lds) {
;     ...
; #pragma unroll
;                     for (int o = 0; o < 16; ++o) { float s = 0.f;
; #pragma unroll
;                         for (int w = 0; w < 8; ++w) s += red[w * 16 + o];
;                         mean[o] = s * (1.0f / 1024.0f); }
;                     __syncthreads();
; #pragma unroll
;                     for (int o = 0; o < 16; ++o) { const float e0 = a0[o] - mean[o], e1 = a1[o] - mean[o]; const float s = wave_sum(e0 * e0 + e1 * e1); if (lane == 0) red[wave * 16 + o] = s; }
.LBB0_423:
	s_or_b64 exec, exec, s[0:1]
	v_add_f32_e32 v97, 0, v97
	v_add_f32_e32 v97, v97, v101
	v_add_f32_e32 v97, v97, v105
	v_add_f32_e32 v97, v97, v109
	v_add_f32_e32 v97, v97, v113
	v_add_f32_e32 v97, v97, v117
	v_add_f32_e32 v97, v97, v121
	v_add_f32_e32 v100, v97, v125
	v_fmac_f32_e32 v207, 0xba800000, v100
	v_fmamk_f32 v97, v100, 0xba800000, v206
	v_mul_f32_e32 v100, v207, v207
	v_fmac_f32_e32 v100, v97, v97
	s_nop 1
	v_add_f32_dpp v100, v100, v100 quad_perm:[1,0,3,2] row_mask:0xf bank_mask:0xf
	s_nop 1
	v_add_f32_dpp v100, v100, v100 quad_perm:[2,3,0,1] row_mask:0xf bank_mask:0xf
	s_nop 1
	v_add_f32_dpp v100, v100, v100 row_half_mirror row_mask:0xf bank_mask:0xf
	s_nop 1
	v_add_f32_dpp v100, v100, v100 row_mirror row_mask:0xf bank_mask:0xf
	ds_bpermute_b32 v101, v242, v100
	s_waitcnt lgkmcnt(0)
	v_add_f32_e32 v100, v100, v101
	ds_bpermute_b32 v101, v243, v100
	s_and_saveexec_b64 s[0:1], s[2:3]
	s_cbranch_execz .LBB0_425
	s_add_i32 s4, s10, 0
	s_waitcnt lgkmcnt(0)
	v_add_f32_e32 v100, v100, v101
	v_mov_b32_e32 v101, s4
	ds_write_b32 v101, v100 offset:4
.LBB0_425:
	s_or_b64 exec, exec, s[0:1]
	v_add_f32_e32 v98, 0, v98
	v_add_f32_e32 v98, v98, v102
	v_add_f32_e32 v98, v98, v106
	v_add_f32_e32 v98, v98, v110
	v_add_f32_e32 v98, v98, v114
	v_add_f32_e32 v98, v98, v118
	v_add_f32_e32 v98, v98, v122
	v_add_f32_e32 v100, v98, v126
	v_fmac_f32_e32 v209, 0xba800000, v100
	v_fmamk_f32 v98, v100, 0xba800000, v208
	v_mul_f32_e32 v100, v209, v209
	v_fmac_f32_e32 v100, v98, v98
	s_waitcnt lgkmcnt(0)
	s_nop 1
	v_add_f32_dpp v100, v100, v100 quad_perm:[1,0,3,2] row_mask:0xf bank_mask:0xf
	s_nop 1
	v_add_f32_dpp v100, v100, v100 quad_perm:[2,3,0,1] row_mask:0xf bank_mask:0xf
	s_nop 1
	v_add_f32_dpp v100, v100, v100 row_half_mirror row_mask:0xf bank_mask:0xf
	s_nop 1
	v_add_f32_dpp v100, v100, v100 row_mirror row_mask:0xf bank_mask:0xf
	ds_bpermute_b32 v101, v242, v100
	s_waitcnt lgkmcnt(0)
	v_add_f32_e32 v100, v100, v101
	ds_bpermute_b32 v101, v243, v100
	s_and_saveexec_b64 s[0:1], s[2:3]
	s_cbranch_execz .LBB0_427
	s_add_i32 s4, s10, 0
	s_waitcnt lgkmcnt(0)
	v_add_f32_e32 v100, v100, v101
	v_mov_b32_e32 v101, s4
	ds_write_b32 v101, v100 offset:8
.LBB0_427:
	s_or_b64 exec, exec, s[0:1]
	v_add_f32_e32 v99, 0, v99
	v_add_f32_e32 v99, v99, v103
	v_add_f32_e32 v99, v99, v107
	v_add_f32_e32 v99, v99, v111
	v_add_f32_e32 v99, v99, v115
	v_add_f32_e32 v99, v99, v119
	v_add_f32_e32 v99, v99, v123
	v_add_f32_e32 v100, v99, v127
	v_fmac_f32_e32 v211, 0xba800000, v100
	v_fmamk_f32 v99, v100, 0xba800000, v210
	v_mul_f32_e32 v100, v211, v211
	v_fmac_f32_e32 v100, v99, v99
	s_waitcnt lgkmcnt(0)
	s_nop 1
	v_add_f32_dpp v100, v100, v100 quad_perm:[1,0,3,2] row_mask:0xf bank_mask:0xf
	s_nop 1
	v_add_f32_dpp v100, v100, v100 quad_perm:[2,3,0,1] row_mask:0xf bank_mask:0xf
	s_nop 1
	v_add_f32_dpp v100, v100, v100 row_half_mirror row_mask:0xf bank_mask:0xf
	s_nop 1
	v_add_f32_dpp v100, v100, v100 row_mirror row_mask:0xf bank_mask:0xf
	ds_bpermute_b32 v101, v242, v100
	s_waitcnt lgkmcnt(0)
	v_add_f32_e32 v100, v100, v101
	ds_bpermute_b32 v101, v243, v100
	s_and_saveexec_b64 s[0:1], s[2:3]
	s_cbranch_execz .LBB0_429
	s_add_i32 s4, s10, 0
	s_waitcnt lgkmcnt(0)
	v_add_f32_e32 v100, v100, v101
	v_mov_b32_e32 v101, s4
	ds_write_b32 v101, v100 offset:12
.LBB0_429:
	s_or_b64 exec, exec, s[0:1]
	v_add_f32_e32 v64, 0, v64
	v_add_f32_e32 v64, v64, v68
	v_add_f32_e32 v64, v64, v72
	v_add_f32_e32 v64, v64, v76
	v_add_f32_e32 v64, v64, v80
	v_add_f32_e32 v64, v64, v84
	v_add_f32_e32 v64, v64, v88
	v_add_f32_e32 v68, v64, v92
	v_fmac_f32_e32 v213, 0xba800000, v68
	v_fmamk_f32 v64, v68, 0xba800000, v212
	v_mul_f32_e32 v68, v213, v213
	v_fmac_f32_e32 v68, v64, v64
	s_nop 1
	v_add_f32_dpp v68, v68, v68 quad_perm:[1,0,3,2] row_mask:0xf bank_mask:0xf
	s_nop 1
	v_add_f32_dpp v68, v68, v68 quad_perm:[2,3,0,1] row_mask:0xf bank_mask:0xf
	s_nop 1
	v_add_f32_dpp v68, v68, v68 row_half_mirror row_mask:0xf bank_mask:0xf
	s_nop 1
	v_add_f32_dpp v68, v68, v68 row_mirror row_mask:0xf bank_mask:0xf
	ds_bpermute_b32 v72, v242, v68
	s_waitcnt lgkmcnt(0)
	v_add_f32_e32 v68, v68, v72
	ds_bpermute_b32 v72, v243, v68
	s_and_saveexec_b64 s[0:1], s[2:3]
	s_cbranch_execz .LBB0_431
	s_add_i32 s4, s10, 0
	s_waitcnt lgkmcnt(0)
	v_add_f32_e32 v68, v68, v72
	v_mov_b32_e32 v72, s4
	ds_write_b32 v72, v68 offset:16
.LBB0_431:
	s_or_b64 exec, exec, s[0:1]
	v_add_f32_e32 v65, 0, v65
	v_add_f32_e32 v65, v65, v69
	v_add_f32_e32 v65, v65, v73
	v_add_f32_e32 v65, v65, v77
	v_add_f32_e32 v65, v65, v81
	v_add_f32_e32 v65, v65, v85
	v_add_f32_e32 v65, v65, v89
	v_add_f32_e32 v68, v65, v93
	v_fmac_f32_e32 v215, 0xba800000, v68
	v_fmamk_f32 v65, v68, 0xba800000, v214
	v_mul_f32_e32 v68, v215, v215
	v_fmac_f32_e32 v68, v65, v65
	s_nop 1
	v_add_f32_dpp v68, v68, v68 quad_perm:[1,0,3,2] row_mask:0xf bank_mask:0xf
	s_nop 1
	v_add_f32_dpp v68, v68, v68 quad_perm:[2,3,0,1] row_mask:0xf bank_mask:0xf
	s_nop 1
	v_add_f32_dpp v68, v68, v68 row_half_mirror row_mask:0xf bank_mask:0xf
	s_nop 1
	v_add_f32_dpp v68, v68, v68 row_mirror row_mask:0xf bank_mask:0xf
	ds_bpermute_b32 v69, v242, v68
	s_waitcnt lgkmcnt(0)
	v_add_f32_e32 v68, v68, v69
	ds_bpermute_b32 v69, v243, v68
	s_and_saveexec_b64 s[0:1], s[2:3]
	s_cbranch_execz .LBB0_433
	s_add_i32 s4, s10, 0
	s_waitcnt lgkmcnt(0)
	v_add_f32_e32 v68, v68, v69
	v_mov_b32_e32 v69, s4
	ds_write_b32 v69, v68 offset:20
; template <int PH>
; __device__ __forceinline__ void run_phase(const Args& args, LAS unsigned char* lds) {
;     ...
; #pragma unroll
;                     for (int o = 0; o < 16; ++o) { float s = 0.f;
; #pragma unroll
;                         for (int w = 0; w < 8; ++w) s += red[w * 16 + o];
;                         mean[o] = s * (1.0f / 1024.0f); }
;                     __syncthreads();
; #pragma unroll
;                     for (int o = 0; o < 16; ++o) { const float e0 = a0[o] - mean[o], e1 = a1[o] - mean[o]; const float s = wave_sum(e0 * e0 + e1 * e1); if (lane == 0) red[wave * 16 + o] = s; }
.LBB0_433:
	s_or_b64 exec, exec, s[0:1]
	v_add_f32_e32 v66, 0, v66
	v_add_f32_e32 v66, v66, v70
	v_add_f32_e32 v66, v66, v74
	v_add_f32_e32 v66, v66, v78
	v_add_f32_e32 v66, v66, v82
	v_add_f32_e32 v66, v66, v86
	v_add_f32_e32 v66, v66, v90
	v_add_f32_e32 v68, v66, v94
	v_fmac_f32_e32 v217, 0xba800000, v68
	v_fmamk_f32 v66, v68, 0xba800000, v216
	v_mul_f32_e32 v68, v217, v217
	v_fmac_f32_e32 v68, v66, v66
	s_waitcnt lgkmcnt(0)
	s_nop 1
	v_add_f32_dpp v68, v68, v68 quad_perm:[1,0,3,2] row_mask:0xf bank_mask:0xf
	s_nop 1
	v_add_f32_dpp v68, v68, v68 quad_perm:[2,3,0,1] row_mask:0xf bank_mask:0xf
	s_nop 1
	v_add_f32_dpp v68, v68, v68 row_half_mirror row_mask:0xf bank_mask:0xf
	s_nop 1
	v_add_f32_dpp v68, v68, v68 row_mirror row_mask:0xf bank_mask:0xf
	ds_bpermute_b32 v69, v242, v68
	s_waitcnt lgkmcnt(0)
	v_add_f32_e32 v68, v68, v69
	ds_bpermute_b32 v69, v243, v68
	s_and_saveexec_b64 s[0:1], s[2:3]
	s_cbranch_execz .LBB0_435
	s_add_i32 s4, s10, 0
	s_waitcnt lgkmcnt(0)
	v_add_f32_e32 v68, v68, v69
	v_mov_b32_e32 v69, s4
	ds_write_b32 v69, v68 offset:24
.LBB0_435:
	s_or_b64 exec, exec, s[0:1]
	v_add_f32_e32 v67, 0, v67
	v_add_f32_e32 v67, v67, v71
	v_add_f32_e32 v67, v67, v75
	v_add_f32_e32 v67, v67, v79
	v_add_f32_e32 v67, v67, v83
	v_add_f32_e32 v67, v67, v87
	v_add_f32_e32 v67, v67, v91
	v_add_f32_e32 v68, v67, v95
	v_fmac_f32_e32 v219, 0xba800000, v68
	v_fmamk_f32 v67, v68, 0xba800000, v218
	v_mul_f32_e32 v68, v219, v219
	v_fmac_f32_e32 v68, v67, v67
	s_waitcnt lgkmcnt(0)
	s_nop 1
	v_add_f32_dpp v68, v68, v68 quad_perm:[1,0,3,2] row_mask:0xf bank_mask:0xf
	s_nop 1
	v_add_f32_dpp v68, v68, v68 quad_perm:[2,3,0,1] row_mask:0xf bank_mask:0xf
	s_nop 1
	v_add_f32_dpp v68, v68, v68 row_half_mirror row_mask:0xf bank_mask:0xf
	s_nop 1
	v_add_f32_dpp v68, v68, v68 row_mirror row_mask:0xf bank_mask:0xf
	ds_bpermute_b32 v69, v242, v68
	s_waitcnt lgkmcnt(0)
	v_add_f32_e32 v68, v68, v69
	ds_bpermute_b32 v69, v243, v68
	s_and_saveexec_b64 s[0:1], s[2:3]
	s_cbranch_execz .LBB0_437
	s_add_i32 s4, s10, 0
	s_waitcnt lgkmcnt(0)
	v_add_f32_e32 v68, v68, v69
	v_mov_b32_e32 v69, s4
	ds_write_b32 v69, v68 offset:28
.LBB0_437:
	s_or_b64 exec, exec, s[0:1]
	v_add_f32_e32 v32, 0, v32
	v_add_f32_e32 v32, v32, v36
	v_add_f32_e32 v32, v32, v40
	v_add_f32_e32 v32, v32, v44
	v_add_f32_e32 v32, v32, v48
	v_add_f32_e32 v32, v32, v52
	v_add_f32_e32 v32, v32, v56
	v_add_f32_e32 v32, v32, v60
	v_fmac_f32_e32 v221, 0xba800000, v32
	v_fmamk_f32 v52, v32, 0xba800000, v220
	v_mul_f32_e32 v32, v221, v221
	v_fmac_f32_e32 v32, v52, v52
	s_nop 1
	v_add_f32_dpp v32, v32, v32 quad_perm:[1,0,3,2] row_mask:0xf bank_mask:0xf
	s_nop 1
	v_add_f32_dpp v32, v32, v32 quad_perm:[2,3,0,1] row_mask:0xf bank_mask:0xf
	s_nop 1
	v_add_f32_dpp v32, v32, v32 row_half_mirror row_mask:0xf bank_mask:0xf
	s_nop 1
	v_add_f32_dpp v32, v32, v32 row_mirror row_mask:0xf bank_mask:0xf
	ds_bpermute_b32 v36, v242, v32
	s_waitcnt lgkmcnt(0)
	v_add_f32_e32 v32, v32, v36
	ds_bpermute_b32 v36, v243, v32
	s_and_saveexec_b64 s[0:1], s[2:3]
	s_cbranch_execz .LBB0_439
	s_add_i32 s4, s10, 0
	s_waitcnt lgkmcnt(0)
	v_add_f32_e32 v32, v32, v36
	v_mov_b32_e32 v36, s4
	ds_write_b32 v36, v32 offset:32
.LBB0_439:
	s_or_b64 exec, exec, s[0:1]
	v_add_f32_e32 v32, 0, v33
	v_add_f32_e32 v32, v32, v37
	v_add_f32_e32 v32, v32, v41
	v_add_f32_e32 v32, v32, v45
	v_add_f32_e32 v32, v32, v49
	v_add_f32_e32 v32, v32, v53
	v_add_f32_e32 v32, v32, v57
	v_add_f32_e32 v32, v32, v61
	v_fmac_f32_e32 v223, 0xba800000, v32
	v_fmamk_f32 v53, v32, 0xba800000, v222
	v_mul_f32_e32 v32, v223, v223
	v_fmac_f32_e32 v32, v53, v53
	s_nop 1
	v_add_f32_dpp v32, v32, v32 quad_perm:[1,0,3,2] row_mask:0xf bank_mask:0xf
	s_nop 1
	v_add_f32_dpp v32, v32, v32 quad_perm:[2,3,0,1] row_mask:0xf bank_mask:0xf
	s_nop 1
	v_add_f32_dpp v32, v32, v32 row_half_mirror row_mask:0xf bank_mask:0xf
	s_nop 1
	v_add_f32_dpp v32, v32, v32 row_mirror row_mask:0xf bank_mask:0xf
	ds_bpermute_b32 v33, v242, v32
	s_waitcnt lgkmcnt(0)
	v_add_f32_e32 v32, v32, v33
	ds_bpermute_b32 v33, v243, v32
	s_and_saveexec_b64 s[0:1], s[2:3]
	s_cbranch_execz .LBB0_441
	s_add_i32 s4, s10, 0
	s_waitcnt lgkmcnt(0)
	v_add_f32_e32 v32, v32, v33
	v_mov_b32_e32 v33, s4
	ds_write_b32 v33, v32 offset:36
.LBB0_441:
	s_or_b64 exec, exec, s[0:1]
	v_add_f32_e32 v32, 0, v34
	v_add_f32_e32 v32, v32, v38
	v_add_f32_e32 v32, v32, v42
	v_add_f32_e32 v32, v32, v46
	v_add_f32_e32 v32, v32, v50
	v_add_f32_e32 v32, v32, v54
	v_add_f32_e32 v32, v32, v58
	v_add_f32_e32 v32, v32, v62
	v_fmac_f32_e32 v225, 0xba800000, v32
	v_fmamk_f32 v54, v32, 0xba800000, v224
	v_mul_f32_e32 v32, v225, v225
	v_fmac_f32_e32 v32, v54, v54
	s_waitcnt lgkmcnt(0)
	s_nop 1
	v_add_f32_dpp v32, v32, v32 quad_perm:[1,0,3,2] row_mask:0xf bank_mask:0xf
	s_nop 1
	v_add_f32_dpp v32, v32, v32 quad_perm:[2,3,0,1] row_mask:0xf bank_mask:0xf
	s_nop 1
	v_add_f32_dpp v32, v32, v32 row_half_mirror row_mask:0xf bank_mask:0xf
	s_nop 1
	v_add_f32_dpp v32, v32, v32 row_mirror row_mask:0xf bank_mask:0xf
	ds_bpermute_b32 v33, v242, v32
	s_waitcnt lgkmcnt(0)
	v_add_f32_e32 v32, v32, v33
	ds_bpermute_b32 v33, v243, v32
	s_and_saveexec_b64 s[0:1], s[2:3]
	s_cbranch_execz .LBB0_443
	s_add_i32 s4, s10, 0
	s_waitcnt lgkmcnt(0)
	v_add_f32_e32 v32, v32, v33
	v_mov_b32_e32 v33, s4
	ds_write_b32 v33, v32 offset:40
; template <int PH>
; __device__ __forceinline__ void run_phase(const Args& args, LAS unsigned char* lds) {
;     ...
; #pragma unroll
;                     for (int o = 0; o < 16; ++o) { float s = 0.f;
; #pragma unroll
;                         for (int w = 0; w < 8; ++w) s += red[w * 16 + o];
;                         mean[o] = s * (1.0f / 1024.0f); }
;                     __syncthreads();
; #pragma unroll
;                     for (int o = 0; o < 16; ++o) { const float e0 = a0[o] - mean[o], e1 = a1[o] - mean[o]; const float s = wave_sum(e0 * e0 + e1 * e1); if (lane == 0) red[wave * 16 + o] = s; }
.LBB0_443:
	s_or_b64 exec, exec, s[0:1]
	v_add_f32_e32 v32, 0, v35
	v_add_f32_e32 v32, v32, v39
	v_add_f32_e32 v32, v32, v43
	v_add_f32_e32 v32, v32, v47
	v_add_f32_e32 v32, v32, v51
	v_add_f32_e32 v32, v32, v55
	v_add_f32_e32 v32, v32, v59
	v_add_f32_e32 v32, v32, v63
	v_fmac_f32_e32 v227, 0xba800000, v32
	v_fmamk_f32 v55, v32, 0xba800000, v226
	v_mul_f32_e32 v32, v227, v227
	v_fmac_f32_e32 v32, v55, v55
	s_waitcnt lgkmcnt(0)
	s_nop 1
	v_add_f32_dpp v32, v32, v32 quad_perm:[1,0,3,2] row_mask:0xf bank_mask:0xf
	s_nop 1
	v_add_f32_dpp v32, v32, v32 quad_perm:[2,3,0,1] row_mask:0xf bank_mask:0xf
	s_nop 1
	v_add_f32_dpp v32, v32, v32 row_half_mirror row_mask:0xf bank_mask:0xf
	s_nop 1
	v_add_f32_dpp v32, v32, v32 row_mirror row_mask:0xf bank_mask:0xf
	ds_bpermute_b32 v33, v242, v32
	s_waitcnt lgkmcnt(0)
	v_add_f32_e32 v32, v32, v33
	ds_bpermute_b32 v33, v243, v32
	s_and_saveexec_b64 s[0:1], s[2:3]
	s_cbranch_execz .LBB0_445
	s_add_i32 s4, s10, 0
	s_waitcnt lgkmcnt(0)
	v_add_f32_e32 v32, v32, v33
	v_mov_b32_e32 v33, s4
	ds_write_b32 v33, v32 offset:44
.LBB0_445:
	s_or_b64 exec, exec, s[0:1]
	v_add_f32_e32 v0, 0, v0
	v_add_f32_e32 v0, v0, v4
	v_add_f32_e32 v0, v0, v8
	v_add_f32_e32 v0, v0, v12
	v_add_f32_e32 v0, v0, v16
	v_add_f32_e32 v0, v0, v20
	v_add_f32_e32 v0, v0, v24
	v_add_f32_e32 v0, v0, v28
	v_fmac_f32_e32 v229, 0xba800000, v0
	v_fmamk_f32 v56, v0, 0xba800000, v228
	v_mul_f32_e32 v0, v229, v229
	v_fmac_f32_e32 v0, v56, v56
	s_nop 1
	v_add_f32_dpp v0, v0, v0 quad_perm:[1,0,3,2] row_mask:0xf bank_mask:0xf
	s_nop 1
	v_add_f32_dpp v0, v0, v0 quad_perm:[2,3,0,1] row_mask:0xf bank_mask:0xf
	s_nop 1
	v_add_f32_dpp v0, v0, v0 row_half_mirror row_mask:0xf bank_mask:0xf
	s_nop 1
	v_add_f32_dpp v0, v0, v0 row_mirror row_mask:0xf bank_mask:0xf
	ds_bpermute_b32 v4, v242, v0
	s_waitcnt lgkmcnt(0)
	v_add_f32_e32 v0, v0, v4
	ds_bpermute_b32 v4, v243, v0
	s_and_saveexec_b64 s[0:1], s[2:3]
	s_cbranch_execz .LBB0_447
	s_add_i32 s4, s10, 0
	s_waitcnt lgkmcnt(0)
	v_add_f32_e32 v0, v0, v4
	v_mov_b32_e32 v4, s4
	ds_write_b32 v4, v0 offset:48
.LBB0_447:
	s_or_b64 exec, exec, s[0:1]
	v_add_f32_e32 v0, 0, v1
	v_add_f32_e32 v0, v0, v5
	v_add_f32_e32 v0, v0, v9
	v_add_f32_e32 v0, v0, v13
	v_add_f32_e32 v0, v0, v17
	v_add_f32_e32 v0, v0, v21
	v_add_f32_e32 v0, v0, v25
	v_add_f32_e32 v0, v0, v29
	v_fmac_f32_e32 v231, 0xba800000, v0
	v_fmamk_f32 v57, v0, 0xba800000, v230
	v_mul_f32_e32 v0, v231, v231
	v_fmac_f32_e32 v0, v57, v57
	s_nop 1
	v_add_f32_dpp v0, v0, v0 quad_perm:[1,0,3,2] row_mask:0xf bank_mask:0xf
	s_nop 1
	v_add_f32_dpp v0, v0, v0 quad_perm:[2,3,0,1] row_mask:0xf bank_mask:0xf
	s_nop 1
	v_add_f32_dpp v0, v0, v0 row_half_mirror row_mask:0xf bank_mask:0xf
	s_nop 1
	v_add_f32_dpp v0, v0, v0 row_mirror row_mask:0xf bank_mask:0xf
	ds_bpermute_b32 v1, v242, v0
	s_waitcnt lgkmcnt(0)
	v_add_f32_e32 v0, v0, v1
	ds_bpermute_b32 v1, v243, v0
	s_and_saveexec_b64 s[0:1], s[2:3]
	s_cbranch_execz .LBB0_449
	s_add_i32 s4, s10, 0
	s_waitcnt lgkmcnt(0)
	v_add_f32_e32 v0, v0, v1
	v_mov_b32_e32 v1, s4
	ds_write_b32 v1, v0 offset:52
.LBB0_449:
	s_or_b64 exec, exec, s[0:1]
	v_add_f32_e32 v0, 0, v2
	v_add_f32_e32 v0, v0, v6
	v_add_f32_e32 v0, v0, v10
	v_add_f32_e32 v0, v0, v14
	v_add_f32_e32 v0, v0, v18
	v_add_f32_e32 v0, v0, v22
	v_add_f32_e32 v0, v0, v26
	v_add_f32_e32 v0, v0, v30
	v_fmac_f32_e32 v233, 0xba800000, v0
	v_fmamk_f32 v58, v0, 0xba800000, v232
	v_mul_f32_e32 v0, v233, v233
	v_fmac_f32_e32 v0, v58, v58
	s_waitcnt lgkmcnt(0)
	s_nop 1
	v_add_f32_dpp v0, v0, v0 quad_perm:[1,0,3,2] row_mask:0xf bank_mask:0xf
	s_nop 1
	v_add_f32_dpp v0, v0, v0 quad_perm:[2,3,0,1] row_mask:0xf bank_mask:0xf
	s_nop 1
	v_add_f32_dpp v0, v0, v0 row_half_mirror row_mask:0xf bank_mask:0xf
	s_nop 1
	v_add_f32_dpp v0, v0, v0 row_mirror row_mask:0xf bank_mask:0xf
	ds_bpermute_b32 v1, v242, v0
	s_waitcnt lgkmcnt(0)
	v_add_f32_e32 v0, v0, v1
	ds_bpermute_b32 v1, v243, v0
	s_and_saveexec_b64 s[0:1], s[2:3]
	s_cbranch_execz .LBB0_451
	s_add_i32 s4, s10, 0
	s_waitcnt lgkmcnt(0)
	v_add_f32_e32 v0, v0, v1
	v_mov_b32_e32 v1, s4
	ds_write_b32 v1, v0 offset:56
.LBB0_451:
	s_or_b64 exec, exec, s[0:1]
	v_add_f32_e32 v0, 0, v3
	v_add_f32_e32 v0, v0, v7
	v_add_f32_e32 v0, v0, v11
	v_add_f32_e32 v0, v0, v15
	v_add_f32_e32 v0, v0, v19
	v_add_f32_e32 v0, v0, v23
	v_add_f32_e32 v0, v0, v27
	v_add_f32_e32 v0, v0, v31
	v_fmac_f32_e32 v235, 0xba800000, v0
	v_fmamk_f32 v59, v0, 0xba800000, v234
	v_mul_f32_e32 v0, v235, v235
	v_fmac_f32_e32 v0, v59, v59
	s_waitcnt lgkmcnt(0)
	s_nop 1
	v_add_f32_dpp v0, v0, v0 quad_perm:[1,0,3,2] row_mask:0xf bank_mask:0xf
	s_nop 1
	v_add_f32_dpp v0, v0, v0 quad_perm:[2,3,0,1] row_mask:0xf bank_mask:0xf
	s_nop 1
	v_add_f32_dpp v0, v0, v0 row_half_mirror row_mask:0xf bank_mask:0xf
	s_nop 1
	v_add_f32_dpp v0, v0, v0 row_mirror row_mask:0xf bank_mask:0xf
	ds_bpermute_b32 v1, v242, v0
	s_waitcnt lgkmcnt(0)
	v_add_f32_e32 v0, v0, v1
	ds_bpermute_b32 v1, v243, v0
	s_and_saveexec_b64 s[0:1], s[2:3]
	s_cbranch_execz .LBB0_298
	s_add_i32 s4, s10, 0
	s_waitcnt lgkmcnt(0)
	v_add_f32_e32 v0, v0, v1
	v_mov_b32_e32 v1, s4
	ds_write_b32 v1, v0 offset:60
	s_branch .LBB0_298

; __device__ __forceinline__ unsigned pk2(float lo, float hi) { return f2bf(lo) | (f2bf(hi) << 16); }
; template <int PH>
; __device__ __forceinline__ void run_phase(const Args& args, LAS unsigned char* lds) {
;     ...
;                     { const u32x2 v = *(const u32x2*)(zkv + lane * 4); const float f0 = bflo(v.x), f1 = bfhi(v.x), f2 = bflo(v.y), f3 = bfhi(v.y);
;                         const float rs = 1.0f / sqrtf(wave_sum(f0 * f0 + f1 * f1 + f2 * f2 + f3 * f3) * (1.0f / 256.0f) + NEPS);
;                         const f32x4 g = *(const f32x4*)(kvg + lane * 4);
;                         u32x2 w; w.x = pk2(f0 * rs * g.x, f1 * rs * g.y); w.y = pk2(f2 * rs * g.z, f3 * rs * g.w);
;                         *(u32x2*)(CKVb + (size_t)row * 256 + lane * 4) = w; }
;                     if (lane < 32) { float x0 = bf2f(zkv[256 + e0]), x1 = bf2f(zkv[256 + e1]);
;                         if (lat) { const float pos = sub ? (float)(t & 63) : (float)(t >> 6); float sn, cs; { const float ang = pos * inv; sn = sinf(ang); cs = cosf(ang); } const float y0 = x0 * cs - x1 * sn, y1 = x0 * sn + x1 * cs; x0 = y0; x1 = y1; }
.LBB0_1143:
	global_load_dwordx2 v[14:15], v26, s[6:7]
	s_nop 0
	global_load_dwordx4 v[32:35], v[6:7], off
	s_lshl_b64 s[8:9], s[0:1], 9
	s_waitcnt vmcnt(0)
	v_lshlrev_b32_e32 v37, 16, v15
	v_lshlrev_b32_e32 v36, 16, v14
	v_and_b32_e32 v15, 0xffff0000, v15
	v_and_b32_e32 v14, 0xffff0000, v14
	v_mov_b32_e32 v38, v15
	v_mov_b32_e32 v39, v37
	v_mul_f32_e32 v2, v36, v36
	v_pk_mul_f32 v[38:39], v[38:39], v[38:39]
	v_fmac_f32_e32 v2, v14, v14
	v_add_f32_e32 v2, v39, v2
	v_add_f32_e32 v2, v38, v2
	ds_bpermute_b32 v38, v18, v2
	v_mov_b32_e32 v39, v34
	s_waitcnt lgkmcnt(0)
	v_add_f32_e32 v2, v2, v38
	s_nop 1
	v_add_f32_dpp v2, v2, v2 quad_perm:[2,3,0,1] row_mask:0xf bank_mask:0xf
	s_nop 1
	v_add_f32_dpp v2, v2, v2 row_half_mirror row_mask:0xf bank_mask:0xf
	s_nop 1
	v_add_f32_dpp v2, v2, v2 row_mirror row_mask:0xf bank_mask:0xf
	ds_bpermute_b32 v38, v22, v2
	s_waitcnt lgkmcnt(0)
	v_add_f32_e32 v2, v2, v38
	ds_bpermute_b32 v38, v23, v2
	s_waitcnt lgkmcnt(0)
	v_add_f32_e32 v2, v2, v38
	v_fmamk_f32 v2, v2, 0x3b800000, v24
	v_mul_f32_e32 v38, 0x4f800000, v2
	v_cmp_gt_f32_e32 vcc, s37, v2
	s_nop 1
	v_cndmask_b32_e32 v2, v2, v38, vcc
	v_sqrt_f32_e32 v40, v2
	v_mov_b32_e32 v38, v32
	v_add_u32_e32 v32, -1, v40
	v_add_u32_e32 v34, 1, v40
	v_fma_f32 v41, -v32, v40, v2
	v_fma_f32 v42, -v34, v40, v2
	v_cmp_ge_f32_e64 s[0:1], 0, v41
	s_nop 1
	v_cndmask_b32_e64 v32, v40, v32, s[0:1]
	v_cmp_lt_f32_e64 s[0:1], 0, v42
	s_nop 1
	v_cndmask_b32_e64 v32, v32, v34, s[0:1]
	v_mul_f32_e32 v34, 0x37800000, v32
	v_cndmask_b32_e32 v32, v32, v34, vcc
	v_cmp_class_f32_e32 vcc, v2, v25
	v_mov_b32_e32 v34, v33
	s_nop 0
	v_cndmask_b32_e32 v2, v32, v2, vcc
	v_div_scale_f32 v32, s[0:1], v2, v2, 1.0
	v_rcp_f32_e32 v40, v32
	v_div_scale_f32 v33, vcc, 1.0, v2, 1.0
	v_fma_f32 v41, -v32, v40, 1.0
	v_fmac_f32_e32 v40, v41, v40
	v_mul_f32_e32 v41, v33, v40
	v_fma_f32 v42, -v32, v41, v33
	v_fmac_f32_e32 v41, v42, v40
	v_fma_f32 v32, -v32, v41, v33
	v_div_fmas_f32 v32, v32, v40, v41
	v_div_fixup_f32 v2, v32, v2, 1.0
	v_pk_mul_f32 v[14:15], v[2:3], v[14:15] op_sel_hi:[0,1]
	v_pk_mul_f32 v[32:33], v[2:3], v[36:37] op_sel_hi:[0,1]
	v_pk_mul_f32 v[14:15], v[34:35], v[14:15]
	v_pk_mul_f32 v[32:33], v[38:39], v[32:33]
	v_and_b32_sdwa v35, v15, v29 dst_sel:DWORD dst_unused:UNUSED_PAD src0_sel:WORD_1 src1_sel:DWORD
	v_and_b32_sdwa v36, v14, v29 dst_sel:DWORD dst_unused:UNUSED_PAD src0_sel:WORD_1 src1_sel:DWORD
	v_and_b32_sdwa v2, v33, v29 dst_sel:DWORD dst_unused:UNUSED_PAD src0_sel:WORD_1 src1_sel:DWORD
	v_and_b32_sdwa v34, v32, v29 dst_sel:DWORD dst_unused:UNUSED_PAD src0_sel:WORD_1 src1_sel:DWORD
	v_add3_u32 v15, v15, v35, s38
	v_add3_u32 v14, v14, v36, s38
	v_add3_u32 v32, v32, v34, s38
	v_add3_u32 v2, v33, v2, s38
	v_and_b32_e32 v15, 0xffff0000, v15
	v_and_b32_e32 v14, 0xffff0000, v14
	v_or_b32_sdwa v15, v15, v2 dst_sel:DWORD dst_unused:UNUSED_PAD src0_sel:DWORD src1_sel:WORD_1
	v_or_b32_sdwa v14, v14, v32 dst_sel:DWORD dst_unused:UNUSED_PAD src0_sel:DWORD src1_sel:WORD_1
	v_lshl_add_u64 v[32:33], v[8:9], 0, s[8:9]
	global_store_dwordx2 v[32:33], v[14:15], off
	s_and_saveexec_b64 s[26:27], s[2:3]
	s_cbranch_execz .LBB0_1134
	v_lshl_add_u64 v[14:15], v[0:1], 1, s[6:7]
	global_load_ushort v2, v[14:15], off offset:544
	s_nop 0
	global_load_ushort v14, v[14:15], off offset:512
	s_and_b32 s51, s12, 0x7ff
	s_andn2_b64 vcc, exec, s[24:25]
	s_waitcnt vmcnt(1)
	v_lshlrev_b32_e32 v15, 16, v2
	s_waitcnt vmcnt(0)
	v_lshlrev_b32_e32 v14, 16, v14
	s_cbranch_vccnz .LBB0_1133
	s_and_b32 s0, s12, 63
	s_lshr_b32 s1, s51, 6
	v_mov_b32_e32 v2, s0
	v_mov_b32_e32 v32, s1
	v_cndmask_b32_e64 v2, v2, v32, s[4:5]
	v_cvt_f32_ubyte0_e32 v2, v2
	v_mul_f32_e32 v32, v17, v2
	v_cmp_ngt_f32_e32 vcc, s39, v32
	s_and_saveexec_b64 s[0:1], vcc
	s_xor_b64 s[28:29], exec, s[0:1]
	s_cbranch_execz .LBB0_1147
	v_lshrrev_b32_e32 v2, 23, v32
	v_add_u32_e32 v2, 0xffffff88, v2
	v_cmp_lt_u32_e64 s[0:1], 63, v2
	s_nop 1
	v_cndmask_b32_e64 v33, 0, v16, s[0:1]
	v_add_u32_e32 v2, v33, v2
	v_cmp_lt_u32_e64 s[6:7], 31, v2
	s_nop 1
	v_cndmask_b32_e64 v33, 0, v30, s[6:7]
	v_add_u32_e32 v2, v33, v2
	v_cmp_lt_u32_e64 s[8:9], 31, v2
	s_nop 1
	v_cndmask_b32_e64 v33, 0, v30, s[8:9]
	v_add_u32_e32 v33, v33, v2
	v_and_b32_e32 v2, 0x7fffff, v32
	v_or_b32_e32 v46, 0x800000, v2
	v_mad_u64_u32 v[34:35], s[10:11], v46, s40, 0
	v_mov_b32_e32 v2, v35
	v_mad_u64_u32 v[36:37], s[10:11], v46, s41, v[2:3]
	v_mov_b32_e32 v2, v37
	v_mad_u64_u32 v[38:39], s[10:11], v46, s42, v[2:3]
	v_mov_b32_e32 v2, v39
	v_mad_u64_u32 v[40:41], s[10:11], v46, s43, v[2:3]
	v_mov_b32_e32 v2, v41
	v_mad_u64_u32 v[42:43], s[10:11], v46, s44, v[2:3]
	v_mov_b32_e32 v2, v43
	v_mad_u64_u32 v[44:45], s[10:11], v46, s45, v[2:3]
	v_mov_b32_e32 v2, v45
	v_mad_u64_u32 v[46:47], s[10:11], v46, s46, v[2:3]
	v_cndmask_b32_e64 v35, v44, v40, s[0:1]
	v_cndmask_b32_e64 v2, v46, v42, s[0:1]
	v_cndmask_b32_e64 v39, v47, v44, s[0:1]
	v_cndmask_b32_e64 v37, v2, v35, s[6:7]
	v_cndmask_b32_e64 v2, v39, v2, s[6:7]
	v_cndmask_b32_e64 v39, v42, v38, s[0:1]
	v_cndmask_b32_e64 v35, v35, v39, s[6:7]
	v_sub_u32_e32 v41, 32, v33
	v_cmp_eq_u32_e64 s[10:11], 0, v33
	v_cndmask_b32_e64 v33, v40, v36, s[0:1]
	v_cndmask_b32_e64 v2, v2, v37, s[8:9]
	v_cndmask_b32_e64 v37, v37, v35, s[8:9]
	v_cndmask_b32_e64 v36, v39, v33, s[6:7]
	v_alignbit_b32 v42, v2, v37, v41
	v_cndmask_b32_e64 v35, v35, v36, s[8:9]
	v_cndmask_b32_e64 v2, v42, v2, s[10:11]
	v_alignbit_b32 v39, v37, v35, v41
	v_cndmask_b32_e64 v34, v38, v34, s[0:1]
	v_cndmask_b32_e64 v37, v39, v37, s[10:11]
	v_bfe_u32 v42, v2, 29, 1
	v_cndmask_b32_e64 v33, v33, v34, s[6:7]
	v_alignbit_b32 v39, v2, v37, 30
	v_sub_u32_e32 v43, 0, v42
	v_cndmask_b32_e64 v33, v36, v33, s[8:9]
	v_xor_b32_e32 v39, v39, v43
	v_alignbit_b32 v34, v35, v33, v41
	v_cndmask_b32_e64 v34, v34, v35, s[10:11]
	v_ffbh_u32_e32 v36, v39
	v_alignbit_b32 v35, v37, v34, 30
	v_min_u32_e32 v36, 32, v36
	v_alignbit_b32 v33, v34, v33, 30
	v_xor_b32_e32 v35, v35, v43
	v_sub_u32_e32 v37, 31, v36
	v_xor_b32_e32 v33, v33, v43
	v_alignbit_b32 v38, v39, v35, v37
	v_alignbit_b32 v33, v35, v33, v37
	v_alignbit_b32 v34, v38, v33, 9
	v_ffbh_u32_e32 v35, v34
	v_min_u32_e32 v35, 32, v35
	v_lshrrev_b32_e32 v40, 29, v2
	v_not_b32_e32 v37, v35
	v_alignbit_b32 v33, v34, v33, v37
	v_lshlrev_b32_e32 v34, 31, v40
	v_or_b32_e32 v37, 0x33000000, v34
	v_add_lshl_u32 v35, v35, v36, 23
	v_lshrrev_b32_e32 v33, 9, v33
	v_sub_u32_e32 v35, v37, v35
	v_or_b32_e32 v34, 0.5, v34
	v_lshlrev_b32_e32 v36, 23, v36
	v_or_b32_e32 v33, v35, v33
	v_lshrrev_b32_e32 v35, 9, v38
	v_sub_u32_e32 v34, v34, v36
	v_or_b32_e32 v34, v35, v34
	v_mul_f32_e32 v35, 0x3fc90fda, v34
	v_fma_f32 v36, v34, s47, -v35
	v_fmac_f32_e32 v36, 0x33a22168, v34
	v_fmac_f32_e32 v36, 0x3fc90fda, v33
	v_lshrrev_b32_e32 v2, 30, v2
	v_add_f32_e32 v34, v35, v36
	v_add_u32_e32 v33, v42, v2

; template <int PH>
; __device__ __forceinline__ void run_phase(const Args& args, LAS unsigned char* lds) {
;     ...
;                 float ss = 0.f;
; #pragma unroll
;                 for (int j = 0; j < 8; ++j) ss += (v[j].x * v[j].x + v[j].y * v[j].y) + (v[j].z * v[j].z + v[j].w * v[j].w);
;                 const float rs = 1.0f / sqrtf(wave_sum(ss) * (1.0f / D) + NEPS);
;                 f32x4* op = (f32x4*)(args.out + (size_t)row * D);
; #pragma unroll
;                 for (int j = 0; j < 8; ++j) { const f32x4 gg = ((const f32x4*)g)[lane + 64 * j]; op[lane + 64 * j] = v[j] * rs * gg; }
.LBB0_1779:
	v_pk_mul_f32 v[100:101], v[60:61], v[60:61]
	v_pk_mul_f32 v[102:103], v[56:57], v[56:57]
	v_pk_mul_f32 v[96:97], v[62:63], v[62:63]
	v_pk_mul_f32 v[98:99], v[58:59], v[58:59]
	v_mov_b32_e32 v104, v100
	v_mov_b32_e32 v105, v102
	v_mov_b32_e32 v102, v101
	v_pk_mul_f32 v[92:93], v[50:51], v[50:51]
	v_pk_mul_f32 v[94:95], v[48:49], v[48:49]
	v_pk_add_f32 v[100:101], v[104:105], v[102:103]
	v_mov_b32_e32 v102, v96
	v_mov_b32_e32 v103, v98
	v_mov_b32_e32 v98, v97
	v_pk_add_f32 v[96:97], v[102:103], v[98:99]
	v_pk_mov_b32 v[98:99], v[94:95], v[92:93] op_sel:[1,0]
	v_mov_b32_e32 v95, v93
	v_pk_add_f32 v[92:93], v[98:99], v[94:95]
	v_pk_add_f32 v[96:97], v[100:101], v[96:97]
	v_pk_add_f32 v[92:93], v[92:93], v[92:93] op_sel_hi:[0,1]
	v_mul_f32_e32 v92, v52, v52
	v_pk_fma_f32 v[94:95], v[52:53], v[52:53], v[92:93] op_sel_hi:[1,1,0]
	v_mul_f32_e32 v92, v54, v54
	v_pk_add_f32 v[96:97], v[96:97], v[96:97] op_sel_hi:[0,1]
	v_pk_fma_f32 v[98:99], v[54:55], v[54:55], v[92:93] op_sel_hi:[1,1,0]
	v_mul_f32_e32 v94, v44, v44
	v_mul_f32_e32 v98, v45, v45
	v_mul_f32_e32 v92, v46, v46
	v_mul_f32_e32 v96, v47, v47
	v_pk_mul_f32 v[88:89], v[42:43], v[42:43]
	v_pk_mul_f32 v[90:91], v[40:41], v[40:41]
	v_pk_add_f32 v[94:95], v[94:95], v[98:99]
	v_pk_add_f32 v[92:93], v[92:93], v[96:97]
	s_add_u32 s6, s6, s8
	v_pk_add_f32 v[92:93], v[94:95], v[92:93]
	v_pk_mov_b32 v[94:95], v[90:91], v[88:89] op_sel:[1,0]
	v_mov_b32_e32 v91, v89
	v_pk_add_f32 v[88:89], v[94:95], v[90:91]
	v_pk_add_f32 v[92:93], v[92:93], v[92:93] op_sel_hi:[0,1]
	v_pk_add_f32 v[88:89], v[88:89], v[88:89] op_sel_hi:[0,1]
	v_mul_f32_e32 v88, v36, v36
	v_pk_fma_f32 v[90:91], v[36:37], v[36:37], v[88:89] op_sel_hi:[1,1,0]
	v_mul_f32_e32 v88, v38, v38
	v_pk_fma_f32 v[94:95], v[38:39], v[38:39], v[88:89] op_sel_hi:[1,1,0]
	v_mul_f32_e32 v90, v84, v84
	v_mul_f32_e32 v94, v85, v85
	v_mul_f32_e32 v88, v86, v86
	v_mul_f32_e32 v92, v87, v87
	global_load_dwordx4 v[84:87], v[66:67], off
	v_pk_add_f32 v[90:91], v[90:91], v[94:95]
	v_pk_add_f32 v[88:89], v[88:89], v[92:93]
	s_addc_u32 s7, s7, s9
	v_pk_add_f32 v[88:89], v[90:91], v[88:89]
	s_nop 0
	v_add_f32_e32 v88, v88, v89
	s_nop 1
	v_add_f32_dpp v88, v88, v88 quad_perm:[1,0,3,2] row_mask:0xf bank_mask:0xf
	s_nop 1
	v_add_f32_dpp v88, v88, v88 quad_perm:[2,3,0,1] row_mask:0xf bank_mask:0xf
	s_nop 1
	v_add_f32_dpp v88, v88, v88 row_half_mirror row_mask:0xf bank_mask:0xf
	s_nop 1
	v_add_f32_dpp v88, v88, v88 row_mirror row_mask:0xf bank_mask:0xf
	ds_bpermute_b32 v89, v82, v88
	s_waitcnt lgkmcnt(0)
	v_add_f32_e32 v88, v88, v89
	ds_bpermute_b32 v89, v83, v88
	s_waitcnt lgkmcnt(0)
	v_add_f32_e32 v88, v88, v89
	v_fmamk_f32 v88, v88, 0x3a000000, v76
	v_mul_f32_e32 v89, 0x4f800000, v88
	v_cmp_gt_f32_e32 vcc, s14, v88
	s_nop 1
	v_cndmask_b32_e32 v88, v88, v89, vcc
	v_sqrt_f32_e32 v89, v88
	s_nop 0
	v_add_u32_e32 v90, -1, v89
	v_fma_f32 v91, -v90, v89, v88
	v_cmp_ge_f32_e64 s[0:1], 0, v91
	v_add_u32_e32 v91, 1, v89
	s_nop 0
	v_cndmask_b32_e64 v90, v89, v90, s[0:1]
	v_fma_f32 v89, -v91, v89, v88
	v_cmp_lt_f32_e64 s[0:1], 0, v89
	s_nop 1
	v_cndmask_b32_e64 v89, v90, v91, s[0:1]
	v_mul_f32_e32 v90, 0x37800000, v89
	v_cndmask_b32_e32 v89, v89, v90, vcc
	v_cmp_class_f32_e32 vcc, v88, v77
	s_nop 1
	v_cndmask_b32_e32 v88, v89, v88, vcc
	v_div_scale_f32 v89, s[0:1], v88, v88, 1.0
	v_rcp_f32_e32 v90, v89
	s_nop 0
	v_fma_f32 v91, -v89, v90, 1.0
	v_fmac_f32_e32 v90, v91, v90
	v_div_scale_f32 v91, vcc, 1.0, v88, 1.0
	v_mul_f32_e32 v92, v91, v90
	v_fma_f32 v93, -v89, v92, v91
	v_fmac_f32_e32 v92, v93, v90
	v_fma_f32 v89, -v89, v92, v91
	v_div_fmas_f32 v89, v89, v90, v92
	v_div_fixup_f32 v92, v89, v88, 1.0
	v_pk_mul_f32 v[60:61], v[60:61], v[92:93] op_sel_hi:[1,0]
	v_pk_mul_f32 v[62:63], v[62:63], v[92:93] op_sel_hi:[1,0]
	s_waitcnt vmcnt(0)
; template <int PH>
; __device__ __forceinline__ void run_phase(const Args& args, LAS unsigned char* lds) {
;     ...
;                 f32x4* op = (f32x4*)(args.out + (size_t)row * D);
; #pragma unroll
;                 for (int j = 0; j < 8; ++j) { const f32x4 gg = ((const f32x4*)g)[lane + 64 * j]; op[lane + 64 * j] = v[j] * rs * gg; }
; #pragma unroll
;                 for (int j = 0; j < 8; ++j) v[j] = nv[j];
	v_pk_mul_f32 v[60:61], v[84:85], v[60:61]
	v_pk_mul_f32 v[62:63], v[86:87], v[62:63]
	v_lshl_add_u64 v[84:85], s[10:11], 0, v[64:65]
	global_store_dwordx4 v[84:85], v[60:63], off
	global_load_dwordx4 v[60:63], v[66:67], off offset:1024
	v_pk_mul_f32 v[58:59], v[58:59], v[92:93] op_sel_hi:[1,0]
	v_pk_mul_f32 v[56:57], v[56:57], v[92:93] op_sel_hi:[1,0]
	v_pk_mul_f32 v[50:51], v[50:51], v[92:93] op_sel_hi:[1,0]
	v_pk_mul_f32 v[48:49], v[48:49], v[92:93] op_sel_hi:[1,0]
	v_pk_mul_f32 v[54:55], v[54:55], v[92:93] op_sel_hi:[1,0]
	v_pk_mul_f32 v[52:53], v[52:53], v[92:93] op_sel_hi:[1,0]
	v_add_co_u32_e32 v94, vcc, s3, v84
	v_pk_mul_f32 v[46:47], v[46:47], v[92:93] op_sel_hi:[1,0]
	v_pk_mul_f32 v[44:45], v[44:45], v[92:93] op_sel_hi:[1,0]
	v_addc_co_u32_e32 v95, vcc, 0, v85, vcc
	v_pk_mul_f32 v[42:43], v[42:43], v[92:93] op_sel_hi:[1,0]
	v_pk_mul_f32 v[40:41], v[40:41], v[92:93] op_sel_hi:[1,0]
	v_pk_mul_f32 v[38:39], v[38:39], v[92:93] op_sel_hi:[1,0]
	v_pk_mul_f32 v[36:37], v[36:37], v[92:93] op_sel_hi:[1,0]
	s_add_u32 s10, s10, s8
	v_pk_mul_f32 v[96:97], v[2:3], v[92:93] op_sel_hi:[1,0]
	v_pk_mul_f32 v[92:93], v[0:1], v[92:93] op_sel_hi:[1,0]
	v_mov_b64_e32 v[0:1], v[20:21]
	s_addc_u32 s11, s11, s9
	v_mov_b32_e32 v86, v22
	s_andn2_b64 vcc, exec, s[12:13]
	v_mov_b64_e32 v[2:3], v[22:23]
	v_mov_b32_e32 v87, v23
	s_waitcnt vmcnt(0)
	v_pk_mul_f32 v[56:57], v[60:61], v[56:57]
	v_pk_mul_f32 v[58:59], v[62:63], v[58:59]
	global_store_dwordx4 v[84:85], v[56:59], off offset:1024
	global_load_dwordx4 v[56:59], v[66:67], off offset:2048
	v_mov_b32_e32 v60, v16
	v_mov_b32_e32 v61, v17
	v_mov_b32_e32 v62, v18
	v_mov_b32_e32 v63, v19
	s_waitcnt vmcnt(0)
	v_pk_mul_f32 v[48:49], v[56:57], v[48:49]
	v_pk_mul_f32 v[50:51], v[58:59], v[50:51]
	global_store_dwordx4 v[84:85], v[48:51], off offset:2048
	global_load_dwordx4 v[48:51], v[66:67], off offset:3072
	v_mov_b32_e32 v56, v12
	v_mov_b32_e32 v57, v13
	v_mov_b32_e32 v58, v14
	v_mov_b32_e32 v59, v15
	s_waitcnt vmcnt(0)
	v_pk_mul_f32 v[48:49], v[48:49], v[52:53]
	v_pk_mul_f32 v[50:51], v[50:51], v[54:55]
	global_store_dwordx4 v[84:85], v[48:51], off offset:3072
	global_load_dwordx4 v[48:51], v[68:69], off
	v_mov_b32_e32 v84, v20
	v_mov_b32_e32 v85, v21
	v_mov_b32_e32 v52, v4
	v_mov_b32_e32 v53, v5
	v_mov_b32_e32 v54, v6
	v_mov_b32_e32 v55, v7
	s_waitcnt vmcnt(0)
	v_pk_mul_f32 v[44:45], v[44:45], v[48:49]
	v_pk_mul_f32 v[46:47], v[46:47], v[50:51]
	global_store_dwordx4 v[94:95], v[44:47], off
	global_load_dwordx4 v[44:47], v[70:71], off
	v_mov_b32_e32 v48, v8
	v_mov_b32_e32 v49, v9
	v_mov_b32_e32 v50, v10
	v_mov_b32_e32 v51, v11
	s_waitcnt vmcnt(0)
	v_pk_mul_f32 v[40:41], v[40:41], v[44:45]
	v_pk_mul_f32 v[42:43], v[42:43], v[46:47]
	global_store_dwordx4 v[94:95], v[40:43], off offset:1024
	global_load_dwordx4 v[40:43], v[72:73], off
	v_mov_b32_e32 v44, v32
	v_mov_b32_e32 v45, v33
	v_mov_b32_e32 v46, v34
	v_mov_b32_e32 v47, v35
	s_waitcnt vmcnt(0)
	v_pk_mul_f32 v[36:37], v[36:37], v[40:41]
	v_pk_mul_f32 v[38:39], v[38:39], v[42:43]
	global_store_dwordx4 v[94:95], v[36:39], off offset:2048
	global_load_dwordx4 v[88:91], v[74:75], off
	v_mov_b32_e32 v40, v28
	v_mov_b32_e32 v41, v29
	v_mov_b32_e32 v42, v30
	v_mov_b32_e32 v43, v31
	v_mov_b32_e32 v36, v24
	v_mov_b32_e32 v37, v25
	v_mov_b32_e32 v38, v26
	v_mov_b32_e32 v39, v27
	s_waitcnt vmcnt(0)
	v_pk_mul_f32 v[88:89], v[92:93], v[88:89]
	v_pk_mul_f32 v[90:91], v[96:97], v[90:91]
	global_store_dwordx4 v[94:95], v[88:91], off offset:3072
	s_cbranch_vccz .LBB0_1782
